# speedup vs baseline: 1.0015x; 1.0015x over previous
; #define STAGE_A(bufoff, gbase) STAGEX(bufoff, gbase, voffA)
; #define STAGE_B(bufoff, gbase) STAGEX(bufoff, gbase, voffB)
; #define LDA(dst, b, h) do { _Pragma("unroll") for (int m = 0; m < 4; ++m) _Pragma("unroll") for (int k = 0; k < 2; ++k) dst[m][k] = *(const __attribute__((address_space(3))) bf16x8*)(lds + SA(b, h) + aoff + m * 2048 + k * 1024); } while (0)
; #define LDB(dst, b, h) do { _Pragma("unroll") for (int n = 0; n < 2; ++n) _Pragma("unroll") for (int k = 0; k < 2; ++k) dst[n][k] = *(const __attribute__((address_space(3))) bf16x8*)(lds + SB_(b, h) + boff + n * 2048 + k * 1024); } while (0)
; #define MMA(ai, bj, At, Bt_) do { __builtin_amdgcn_s_setprio(1); _Pragma("unroll") for (int m = 0; m < 4; ++m) _Pragma("unroll") for (int n = 0; n < 2; ++n) _Pragma("unroll") for (int k = 0; k < 2; ++k) \
;       acc[ai][bj][m][n] = __builtin_amdgcn_mfma_f32_16x16x32_bf16(Bt_[n][k], At[m][k], acc[ai][bj][m][n], 0, 0, 0); \
;     __builtin_amdgcn_s_setprio(0); } while (0)
; #define WAIT_V(n) asm volatile("s_waitcnt vmcnt(" #n ")" ::: "memory")
; #define BAR __builtin_amdgcn_s_barrier()
; template <int MODE>
; DEV void gemm_phase(const bf16_t* __restrict__ A, const bf16_t* __restrict__ Bt, int M, int N, int K, bf16_t* __restrict__ Out, int ldo,
;                     const float* __restrict__ rstd, const float* __restrict__ rope) {
;     ...
;     for (int t = 0; t < nt; t += 2) {
;       const bool last = (t == nt - 2);
;       const char* a1 = cA + (size_t)(t + 1) * 128;
;       const char* a2 = last ? nA : cA + (size_t)(t + 2) * 128; const char* b2 = last ? nB : cB + (size_t)(t + 2) * 128;
;       const char* a3 = a2 + 128; const char* b3 = b2 + 128;
;       LDB(B0, 0, 0); LDB(B1, 0, 1); SCHED; LDA(At, 0, 0); STAGE_A(SA(1, 1), a1 + hstep);
;       WAIT_V(8); WAIT_L(0); BAR; MMA(0, 0, At, B0); MMA(0, 1, At, B1); BAR; SCHED;
;       LDA(At, 0, 1); STAGE_B(SB_(0, 0), b2); STAGE_B(SB_(0, 1), b2 + hstep); STAGE_A(SA(0, 0), a2);
;       WAIT_V(8); WAIT_L(0); BAR; MMA(1, 0, At, B0); MMA(1, 1, At, B1); BAR; SCHED;
;       LDB(B0, 1, 0); LDB(B1, 1, 1); SCHED; LDA(At, 1, 0); STAGE_A(SA(0, 1), a2 + hstep);
;       WAIT_V(8); WAIT_L(0); BAR; MMA(0, 0, At, B0); MMA(0, 1, At, B1); BAR; SCHED;
;       LDA(At, 1, 1); STAGE_B(SB_(1, 0), b3); STAGE_B(SB_(1, 1), b3 + hstep); STAGE_A(SA(1, 0), a3);
;       WAIT_V(8); WAIT_L(0); BAR; MMA(1, 0, At, B0); MMA(1, 1, At, B1); BAR; SCHED;
.LBB0_128:
	s_add_u32 s26, s44, s8
	s_addc_u32 s27, s45, s9
	s_add_u32 s26, s26, 0x12200100
	s_addc_u32 s27, s27, 0
	s_add_u32 s49, s46, s8
	s_addc_u32 s50, s47, s9
	s_add_i32 s51, 0, 0x10000
	s_cmpk_eq_i32 s8, 0xf00
	s_cselect_b32 s29, s42, s27
	s_cselect_b32 s28, s19, s26
	s_cselect_b32 s27, s43, s50
	s_cselect_b32 s26, s21, s49
	s_add_i32 s49, 0, 0x14000
	v_add_u32_e32 v144, s51, v171
	v_add_u32_e32 v168, s49, v171
	ds_read_b128 v[132:135], v144
	ds_read_b128 v[136:139], v144 offset:1024
	ds_read_b128 v[140:143], v144 offset:2048
	ds_read_b128 v[144:147], v144 offset:3072
	ds_read_b128 v[148:151], v168
	ds_read_b128 v[164:167], v168 offset:1024
	ds_read_b128 v[174:177], v168 offset:2048
	ds_read_b128 v[178:181], v168 offset:3072
	v_lshl_add_u64 v[168:169], v[128:129], 0, s[8:9]
	s_add_i32 m0, s31, 0xc000
	ds_read_b128 v[182:185], v172
	ds_read_b128 v[186:189], v172 offset:1024
	ds_read_b128 v[194:197], v172 offset:2048
	ds_read_b128 v[198:201], v172 offset:3072
	ds_read_b128 v[202:205], v172 offset:4096
	ds_read_b128 v[206:209], v172 offset:5120
	ds_read_b128 v[216:219], v172 offset:6144
	ds_read_b128 v[220:223], v172 offset:7168
	global_load_lds_dwordx4 v[168:169], off
	v_lshl_add_u64 v[168:169], v[130:131], 0, s[8:9]
	s_add_i32 m0, s31, 0xe000
	s_nop 0
	global_load_lds_dwordx4 v[168:169], off
	s_waitcnt vmcnt(8)
	s_waitcnt lgkmcnt(0)
	s_setprio 1
	s_barrier
	v_mfma_f32_16x16x32_bf16 v[124:127], v[132:135], v[182:185], v[124:127]
	v_mfma_f32_16x16x32_bf16 v[120:123], v[140:143], v[182:185], v[120:123]
	v_mfma_f32_16x16x32_bf16 v[108:111], v[132:135], v[194:197], v[108:111]
	v_mfma_f32_16x16x32_bf16 v[104:107], v[140:143], v[194:197], v[104:107]
	v_mfma_f32_16x16x32_bf16 v[92:95], v[132:135], v[202:205], v[92:95]
	v_mfma_f32_16x16x32_bf16 v[88:91], v[140:143], v[202:205], v[88:91]
	v_mfma_f32_16x16x32_bf16 v[76:79], v[132:135], v[216:219], v[76:79]
	v_mfma_f32_16x16x32_bf16 v[72:75], v[140:143], v[216:219], v[72:75]
	v_mfma_f32_16x16x32_bf16 v[124:127], v[136:139], v[186:189], v[124:127]
	v_mfma_f32_16x16x32_bf16 v[120:123], v[144:147], v[186:189], v[120:123]
	v_mfma_f32_16x16x32_bf16 v[108:111], v[136:139], v[198:201], v[108:111]
	v_mfma_f32_16x16x32_bf16 v[104:107], v[144:147], v[198:201], v[104:107]
	v_mfma_f32_16x16x32_bf16 v[92:95], v[136:139], v[206:209], v[92:95]
	v_mfma_f32_16x16x32_bf16 v[88:91], v[144:147], v[206:209], v[88:91]
	v_mfma_f32_16x16x32_bf16 v[76:79], v[136:139], v[220:223], v[76:79]
	v_mfma_f32_16x16x32_bf16 v[72:75], v[144:147], v[220:223], v[72:75]
	v_mfma_f32_16x16x32_bf16 v[116:119], v[148:151], v[182:185], v[116:119]
	v_mfma_f32_16x16x32_bf16 v[112:115], v[174:177], v[182:185], v[112:115]
	v_mfma_f32_16x16x32_bf16 v[100:103], v[148:151], v[194:197], v[100:103]
	v_mfma_f32_16x16x32_bf16 v[96:99], v[174:177], v[194:197], v[96:99]
	v_mfma_f32_16x16x32_bf16 v[84:87], v[148:151], v[202:205], v[84:87]
	v_mfma_f32_16x16x32_bf16 v[80:83], v[174:177], v[202:205], v[80:83]
	v_mfma_f32_16x16x32_bf16 v[68:71], v[148:151], v[216:219], v[68:71]
	v_mfma_f32_16x16x32_bf16 v[64:67], v[174:177], v[216:219], v[64:67]
	v_mfma_f32_16x16x32_bf16 v[116:119], v[164:167], v[186:189], v[116:119]
	v_mfma_f32_16x16x32_bf16 v[112:115], v[178:181], v[186:189], v[112:115]
	v_mfma_f32_16x16x32_bf16 v[100:103], v[164:167], v[198:201], v[100:103]
	v_mfma_f32_16x16x32_bf16 v[96:99], v[178:181], v[198:201], v[96:99]
	v_mfma_f32_16x16x32_bf16 v[84:87], v[164:167], v[206:209], v[84:87]
	v_mfma_f32_16x16x32_bf16 v[80:83], v[178:181], v[206:209], v[80:83]
	v_mfma_f32_16x16x32_bf16 v[68:71], v[164:167], v[220:223], v[68:71]
	v_mfma_f32_16x16x32_bf16 v[64:67], v[178:181], v[220:223], v[64:67]
	s_setprio 0
	s_barrier
	s_add_i32 s50, s51, s30
	v_lshl_add_u64 v[168:169], s[26:27], 0, v[192:193]
	s_mov_b32 m0, s50
	ds_read_b128 v[182:185], v172 offset:16384
	ds_read_b128 v[186:189], v172 offset:17408
	ds_read_b128 v[194:197], v172 offset:18432
	ds_read_b128 v[198:201], v172 offset:19456
	ds_read_b128 v[202:205], v172 offset:20480
	ds_read_b128 v[206:209], v172 offset:21504
	ds_read_b128 v[216:219], v172 offset:22528
	ds_read_b128 v[220:223], v172 offset:23552
	global_load_lds_dwordx4 v[168:169], off
	s_add_i32 m0, s50, 0x2000
	s_add_u32 s50, s26, 0x80000
	v_lshl_add_u64 v[190:191], s[26:27], 0, v[152:153]
	s_addc_u32 s51, s27, 0
	s_add_i32 s49, s49, s30
	global_load_lds_dwordx4 v[190:191], off
	v_lshl_add_u64 v[212:213], s[50:51], 0, v[192:193]
	s_mov_b32 m0, s49
	v_lshl_add_u64 v[214:215], s[28:29], 0, v[154:155]
	global_load_lds_dwordx4 v[212:213], off
	v_lshl_add_u64 v[212:213], s[50:51], 0, v[152:153]
	s_add_i32 m0, s49, 0x2000
	s_nop 0
	global_load_lds_dwordx4 v[212:213], off
	v_lshl_add_u64 v[212:213], s[28:29], 0, v[156:157]
	s_mov_b32 m0, s31
	s_nop 0
	global_load_lds_dwordx4 v[212:213], off
	s_mov_b32 m0, s34
	s_nop 0
	global_load_lds_dwordx4 v[214:215], off
	s_waitcnt vmcnt(8)
	s_waitcnt lgkmcnt(0)
	s_setprio 1
	s_barrier
; #define STAGE_A(bufoff, gbase) STAGEX(bufoff, gbase, voffA)
; #define STAGE_B(bufoff, gbase) STAGEX(bufoff, gbase, voffB)
; #define LDA(dst, b, h) do { _Pragma("unroll") for (int m = 0; m < 4; ++m) _Pragma("unroll") for (int k = 0; k < 2; ++k) dst[m][k] = *(const __attribute__((address_space(3))) bf16x8*)(lds + SA(b, h) + aoff + m * 2048 + k * 1024); } while (0)
; #define LDB(dst, b, h) do { _Pragma("unroll") for (int n = 0; n < 2; ++n) _Pragma("unroll") for (int k = 0; k < 2; ++k) dst[n][k] = *(const __attribute__((address_space(3))) bf16x8*)(lds + SB_(b, h) + boff + n * 2048 + k * 1024); } while (0)
; #define MMA(ai, bj, At, Bt_) do { __builtin_amdgcn_s_setprio(1); _Pragma("unroll") for (int m = 0; m < 4; ++m) _Pragma("unroll") for (int n = 0; n < 2; ++n) _Pragma("unroll") for (int k = 0; k < 2; ++k) \
;       acc[ai][bj][m][n] = __builtin_amdgcn_mfma_f32_16x16x32_bf16(Bt_[n][k], At[m][k], acc[ai][bj][m][n], 0, 0, 0); \
;     __builtin_amdgcn_s_setprio(0); } while (0)
; #define WAIT_V(n) asm volatile("s_waitcnt vmcnt(" #n ")" ::: "memory")
; #define BAR __builtin_amdgcn_s_barrier()
; template <int MODE>
; DEV void gemm_phase(const bf16_t* __restrict__ A, const bf16_t* __restrict__ Bt, int M, int N, int K, bf16_t* __restrict__ Out, int ldo,
;                     const float* __restrict__ rstd, const float* __restrict__ rope) {
;     ...
;     for (int t = 0; t < nt; t += 2) {
;       const bool last = (t == nt - 2);
;       const char* a1 = cA + (size_t)(t + 1) * 128;
;       const char* a2 = last ? nA : cA + (size_t)(t + 2) * 128; const char* b2 = last ? nB : cB + (size_t)(t + 2) * 128;
;       const char* a3 = a2 + 128; const char* b3 = b2 + 128;
;       LDB(B0, 0, 0); LDB(B1, 0, 1); SCHED; LDA(At, 0, 0); STAGE_A(SA(1, 1), a1 + hstep);
;       WAIT_V(8); WAIT_L(0); BAR; MMA(0, 0, At, B0); MMA(0, 1, At, B1); BAR; SCHED;
;       LDA(At, 0, 1); STAGE_B(SB_(0, 0), b2); STAGE_B(SB_(0, 1), b2 + hstep); STAGE_A(SA(0, 0), a2);
;       WAIT_V(8); WAIT_L(0); BAR; MMA(1, 0, At, B0); MMA(1, 1, At, B1); BAR; SCHED;
;       LDB(B0, 1, 0); LDB(B1, 1, 1); SCHED; LDA(At, 1, 0); STAGE_A(SA(0, 1), a2 + hstep);
;       WAIT_V(8); WAIT_L(0); BAR; MMA(0, 0, At, B0); MMA(0, 1, At, B1); BAR; SCHED;
;       LDA(At, 1, 1); STAGE_B(SB_(1, 0), b3); STAGE_B(SB_(1, 1), b3 + hstep); STAGE_A(SA(1, 0), a3);
;       WAIT_V(8); WAIT_L(0); BAR; MMA(1, 0, At, B0); MMA(1, 1, At, B1); BAR; SCHED;
	v_mfma_f32_16x16x32_bf16 v[60:63], v[132:135], v[182:185], v[60:63]
	v_mfma_f32_16x16x32_bf16 v[56:59], v[140:143], v[182:185], v[56:59]
	v_mfma_f32_16x16x32_bf16 v[44:47], v[132:135], v[194:197], v[44:47]
	v_mfma_f32_16x16x32_bf16 v[40:43], v[140:143], v[194:197], v[40:43]
	v_mfma_f32_16x16x32_bf16 v[28:31], v[132:135], v[202:205], v[28:31]
	v_mfma_f32_16x16x32_bf16 v[24:27], v[140:143], v[202:205], v[24:27]
	v_mfma_f32_16x16x32_bf16 v[12:15], v[132:135], v[216:219], v[12:15]
	v_mfma_f32_16x16x32_bf16 v[8:11], v[140:143], v[216:219], v[8:11]
	v_mfma_f32_16x16x32_bf16 v[60:63], v[136:139], v[186:189], v[60:63]
	v_mfma_f32_16x16x32_bf16 v[56:59], v[144:147], v[186:189], v[56:59]
	v_mfma_f32_16x16x32_bf16 v[44:47], v[136:139], v[198:201], v[44:47]
	v_mfma_f32_16x16x32_bf16 v[40:43], v[144:147], v[198:201], v[40:43]
	v_mfma_f32_16x16x32_bf16 v[28:31], v[136:139], v[206:209], v[28:31]
	v_mfma_f32_16x16x32_bf16 v[24:27], v[144:147], v[206:209], v[24:27]
	v_mfma_f32_16x16x32_bf16 v[12:15], v[136:139], v[220:223], v[12:15]
	v_mfma_f32_16x16x32_bf16 v[8:11], v[144:147], v[220:223], v[8:11]
	v_mfma_f32_16x16x32_bf16 v[52:55], v[148:151], v[182:185], v[52:55]
	v_mfma_f32_16x16x32_bf16 v[48:51], v[174:177], v[182:185], v[48:51]
	v_mfma_f32_16x16x32_bf16 v[36:39], v[148:151], v[194:197], v[36:39]
	v_mfma_f32_16x16x32_bf16 v[32:35], v[174:177], v[194:197], v[32:35]
	v_mfma_f32_16x16x32_bf16 v[20:23], v[148:151], v[202:205], v[20:23]
	v_mfma_f32_16x16x32_bf16 v[16:19], v[174:177], v[202:205], v[16:19]
	v_mfma_f32_16x16x32_bf16 v[4:7], v[148:151], v[216:219], v[4:7]
	v_mfma_f32_16x16x32_bf16 v[0:3], v[174:177], v[216:219], v[0:3]
	v_mfma_f32_16x16x32_bf16 v[52:55], v[164:167], v[186:189], v[52:55]
	v_mfma_f32_16x16x32_bf16 v[48:51], v[178:181], v[186:189], v[48:51]
	v_mfma_f32_16x16x32_bf16 v[36:39], v[164:167], v[198:201], v[36:39]
	v_mfma_f32_16x16x32_bf16 v[32:35], v[178:181], v[198:201], v[32:35]
	v_mfma_f32_16x16x32_bf16 v[20:23], v[164:167], v[206:209], v[20:23]
	v_mfma_f32_16x16x32_bf16 v[16:19], v[178:181], v[206:209], v[16:19]
	v_mfma_f32_16x16x32_bf16 v[4:7], v[164:167], v[220:223], v[4:7]
	v_mfma_f32_16x16x32_bf16 v[0:3], v[178:181], v[220:223], v[0:3]
	s_setprio 0
	s_barrier
	s_add_i32 s49, 0, 0x18000
	s_add_i32 s50, 0, 0x1c000
	v_add_u32_e32 v144, s49, v171
	v_add_u32_e32 v173, s50, v171
	ds_read_b128 v[132:135], v144
	ds_read_b128 v[136:139], v144 offset:1024
	ds_read_b128 v[140:143], v144 offset:2048
	ds_read_b128 v[144:147], v144 offset:3072
	ds_read_b128 v[148:151], v173
	ds_read_b128 v[164:167], v173 offset:1024
	ds_read_b128 v[174:177], v173 offset:2048
	ds_read_b128 v[178:181], v173 offset:3072
	s_add_u32 s28, s28, 0x80000
	s_addc_u32 s29, s29, 0
	s_mov_b32 m0, s35
	v_lshl_add_u64 v[224:225], s[28:29], 0, v[156:157]
	ds_read_b128 v[182:185], v172 offset:32768
	ds_read_b128 v[186:189], v172 offset:33792
	ds_read_b128 v[194:197], v172 offset:34816
	ds_read_b128 v[198:201], v172 offset:35840
	ds_read_b128 v[202:205], v172 offset:36864
	ds_read_b128 v[206:209], v172 offset:37888
	ds_read_b128 v[216:219], v172 offset:38912
	ds_read_b128 v[220:223], v172 offset:39936
	global_load_lds_dwordx4 v[224:225], off
	v_lshl_add_u64 v[224:225], s[28:29], 0, v[154:155]
	s_mov_b32 m0, s36
	s_nop 0
	global_load_lds_dwordx4 v[224:225], off
	s_waitcnt vmcnt(8)
	s_waitcnt lgkmcnt(0)
	s_setprio 1
	s_barrier
	v_mfma_f32_16x16x32_bf16 v[124:127], v[132:135], v[182:185], v[124:127]
	v_mfma_f32_16x16x32_bf16 v[120:123], v[140:143], v[182:185], v[120:123]
	v_mfma_f32_16x16x32_bf16 v[108:111], v[132:135], v[194:197], v[108:111]
	v_mfma_f32_16x16x32_bf16 v[104:107], v[140:143], v[194:197], v[104:107]
	v_mfma_f32_16x16x32_bf16 v[92:95], v[132:135], v[202:205], v[92:95]
	v_mfma_f32_16x16x32_bf16 v[88:91], v[140:143], v[202:205], v[88:91]
	v_mfma_f32_16x16x32_bf16 v[76:79], v[132:135], v[216:219], v[76:79]
	v_mfma_f32_16x16x32_bf16 v[72:75], v[140:143], v[216:219], v[72:75]
	v_mfma_f32_16x16x32_bf16 v[124:127], v[136:139], v[186:189], v[124:127]
	v_mfma_f32_16x16x32_bf16 v[120:123], v[144:147], v[186:189], v[120:123]
	v_mfma_f32_16x16x32_bf16 v[108:111], v[136:139], v[198:201], v[108:111]
	v_mfma_f32_16x16x32_bf16 v[104:107], v[144:147], v[198:201], v[104:107]
	v_mfma_f32_16x16x32_bf16 v[92:95], v[136:139], v[206:209], v[92:95]
	v_mfma_f32_16x16x32_bf16 v[88:91], v[144:147], v[206:209], v[88:91]
	v_mfma_f32_16x16x32_bf16 v[76:79], v[136:139], v[220:223], v[76:79]
	v_mfma_f32_16x16x32_bf16 v[72:75], v[144:147], v[220:223], v[72:75]
	v_mfma_f32_16x16x32_bf16 v[116:119], v[148:151], v[182:185], v[116:119]
	v_mfma_f32_16x16x32_bf16 v[112:115], v[174:177], v[182:185], v[112:115]
	v_mfma_f32_16x16x32_bf16 v[100:103], v[148:151], v[194:197], v[100:103]
	v_mfma_f32_16x16x32_bf16 v[96:99], v[174:177], v[194:197], v[96:99]
	v_mfma_f32_16x16x32_bf16 v[84:87], v[148:151], v[202:205], v[84:87]
	v_mfma_f32_16x16x32_bf16 v[80:83], v[174:177], v[202:205], v[80:83]
	v_mfma_f32_16x16x32_bf16 v[68:71], v[148:151], v[216:219], v[68:71]
	v_mfma_f32_16x16x32_bf16 v[64:67], v[174:177], v[216:219], v[64:67]
	v_mfma_f32_16x16x32_bf16 v[116:119], v[164:167], v[186:189], v[116:119]
	v_mfma_f32_16x16x32_bf16 v[112:115], v[178:181], v[186:189], v[112:115]
	v_mfma_f32_16x16x32_bf16 v[100:103], v[164:167], v[198:201], v[100:103]
	v_mfma_f32_16x16x32_bf16 v[96:99], v[178:181], v[198:201], v[96:99]
	v_mfma_f32_16x16x32_bf16 v[84:87], v[164:167], v[206:209], v[84:87]
	v_mfma_f32_16x16x32_bf16 v[80:83], v[178:181], v[206:209], v[80:83]
	v_mfma_f32_16x16x32_bf16 v[68:71], v[164:167], v[220:223], v[68:71]
	v_mfma_f32_16x16x32_bf16 v[64:67], v[178:181], v[220:223], v[64:67]
	s_setprio 0
	s_barrier
; #define STAGE_A(bufoff, gbase) STAGEX(bufoff, gbase, voffA)
; #define STAGE_B(bufoff, gbase) STAGEX(bufoff, gbase, voffB)
; #define LDA(dst, b, h) do { _Pragma("unroll") for (int m = 0; m < 4; ++m) _Pragma("unroll") for (int k = 0; k < 2; ++k) dst[m][k] = *(const __attribute__((address_space(3))) bf16x8*)(lds + SA(b, h) + aoff + m * 2048 + k * 1024); } while (0)
; #define LDB(dst, b, h) do { _Pragma("unroll") for (int n = 0; n < 2; ++n) _Pragma("unroll") for (int k = 0; k < 2; ++k) dst[n][k] = *(const __attribute__((address_space(3))) bf16x8*)(lds + SB_(b, h) + boff + n * 2048 + k * 1024); } while (0)
; #define MMA(ai, bj, At, Bt_) do { __builtin_amdgcn_s_setprio(1); _Pragma("unroll") for (int m = 0; m < 4; ++m) _Pragma("unroll") for (int n = 0; n < 2; ++n) _Pragma("unroll") for (int k = 0; k < 2; ++k) \
;       acc[ai][bj][m][n] = __builtin_amdgcn_mfma_f32_16x16x32_bf16(Bt_[n][k], At[m][k], acc[ai][bj][m][n], 0, 0, 0); \
;     __builtin_amdgcn_s_setprio(0); } while (0)
; #define WAIT_V(n) asm volatile("s_waitcnt vmcnt(" #n ")" ::: "memory")
; #define BAR __builtin_amdgcn_s_barrier()
; template <int MODE>
; DEV void gemm_phase(const bf16_t* __restrict__ A, const bf16_t* __restrict__ Bt, int M, int N, int K, bf16_t* __restrict__ Out, int ldo,
;                     const float* __restrict__ rstd, const float* __restrict__ rope) {
;     ...
;     for (int t = 0; t < nt; t += 2) {
;       const bool last = (t == nt - 2);
;       const char* a1 = cA + (size_t)(t + 1) * 128;
;       const char* a2 = last ? nA : cA + (size_t)(t + 2) * 128; const char* b2 = last ? nB : cB + (size_t)(t + 2) * 128;
;       const char* a3 = a2 + 128; const char* b3 = b2 + 128;
;       LDB(B0, 0, 0); LDB(B1, 0, 1); SCHED; LDA(At, 0, 0); STAGE_A(SA(1, 1), a1 + hstep);
;       WAIT_V(8); WAIT_L(0); BAR; MMA(0, 0, At, B0); MMA(0, 1, At, B1); BAR; SCHED;
;       LDA(At, 0, 1); STAGE_B(SB_(0, 0), b2); STAGE_B(SB_(0, 1), b2 + hstep); STAGE_A(SA(0, 0), a2);
;       WAIT_V(8); WAIT_L(0); BAR; MMA(1, 0, At, B0); MMA(1, 1, At, B1); BAR; SCHED;
;       LDB(B0, 1, 0); LDB(B1, 1, 1); SCHED; LDA(At, 1, 0); STAGE_A(SA(0, 1), a2 + hstep);
;       WAIT_V(8); WAIT_L(0); BAR; MMA(0, 0, At, B0); MMA(0, 1, At, B1); BAR; SCHED;
;       LDA(At, 1, 1); STAGE_B(SB_(1, 0), b3); STAGE_B(SB_(1, 1), b3 + hstep); STAGE_A(SA(1, 0), a3);
;       WAIT_V(8); WAIT_L(0); BAR; MMA(1, 0, At, B0); MMA(1, 1, At, B1); BAR; SCHED;
	s_add_i32 s28, s49, s30
	v_lshl_add_u64 v[168:169], v[168:169], 0, s[88:89]
	s_mov_b32 m0, s28
	ds_read_b128 v[182:185], v172 offset:49152
	ds_read_b128 v[186:189], v172 offset:50176
	ds_read_b128 v[194:197], v172 offset:51200
	ds_read_b128 v[198:201], v172 offset:52224
	ds_read_b128 v[202:205], v172 offset:53248
	ds_read_b128 v[206:209], v172 offset:54272
	ds_read_b128 v[216:219], v172 offset:55296
	ds_read_b128 v[220:223], v172 offset:56320
	global_load_lds_dwordx4 v[168:169], off
	s_add_i32 m0, s28, 0x2000
	s_add_u32 s26, s26, 0x80080
	v_lshl_add_u64 v[168:169], v[190:191], 0, s[88:89]
	s_addc_u32 s27, s27, 0
	s_add_i32 s28, s50, s30
	global_load_lds_dwordx4 v[168:169], off
	v_lshl_add_u64 v[168:169], s[26:27], 0, v[192:193]
	s_mov_b32 m0, s28
	s_nop 0
	global_load_lds_dwordx4 v[168:169], off
	v_lshl_add_u64 v[168:169], s[26:27], 0, v[152:153]
	s_add_i32 m0, s28, 0x2000
	s_nop 0
	global_load_lds_dwordx4 v[168:169], off
	v_lshl_add_u64 v[168:169], v[212:213], 0, s[88:89]
	s_mov_b32 m0, s37
	s_nop 0
	global_load_lds_dwordx4 v[168:169], off
	v_lshl_add_u64 v[168:169], v[214:215], 0, s[88:89]
	s_mov_b32 m0, s38
	s_nop 0
	global_load_lds_dwordx4 v[168:169], off
	s_waitcnt vmcnt(8)
	s_waitcnt lgkmcnt(0)
	s_setprio 1
	s_barrier
	v_mfma_f32_16x16x32_bf16 v[60:63], v[132:135], v[182:185], v[60:63]
	v_mfma_f32_16x16x32_bf16 v[56:59], v[140:143], v[182:185], v[56:59]
	v_mfma_f32_16x16x32_bf16 v[44:47], v[132:135], v[194:197], v[44:47]
	v_mfma_f32_16x16x32_bf16 v[40:43], v[140:143], v[194:197], v[40:43]
	v_mfma_f32_16x16x32_bf16 v[28:31], v[132:135], v[202:205], v[28:31]
	v_mfma_f32_16x16x32_bf16 v[24:27], v[140:143], v[202:205], v[24:27]
	v_mfma_f32_16x16x32_bf16 v[12:15], v[132:135], v[216:219], v[12:15]
	v_mfma_f32_16x16x32_bf16 v[8:11], v[140:143], v[216:219], v[8:11]
	v_mfma_f32_16x16x32_bf16 v[60:63], v[136:139], v[186:189], v[60:63]
	v_mfma_f32_16x16x32_bf16 v[56:59], v[144:147], v[186:189], v[56:59]
	v_mfma_f32_16x16x32_bf16 v[44:47], v[136:139], v[198:201], v[44:47]
	v_mfma_f32_16x16x32_bf16 v[40:43], v[144:147], v[198:201], v[40:43]
	v_mfma_f32_16x16x32_bf16 v[28:31], v[136:139], v[206:209], v[28:31]
	v_mfma_f32_16x16x32_bf16 v[24:27], v[144:147], v[206:209], v[24:27]
	v_mfma_f32_16x16x32_bf16 v[12:15], v[136:139], v[220:223], v[12:15]
	v_mfma_f32_16x16x32_bf16 v[8:11], v[144:147], v[220:223], v[8:11]
	v_mfma_f32_16x16x32_bf16 v[52:55], v[148:151], v[182:185], v[52:55]
	v_mfma_f32_16x16x32_bf16 v[48:51], v[174:177], v[182:185], v[48:51]
	v_mfma_f32_16x16x32_bf16 v[36:39], v[148:151], v[194:197], v[36:39]
	v_mfma_f32_16x16x32_bf16 v[32:35], v[174:177], v[194:197], v[32:35]
	v_mfma_f32_16x16x32_bf16 v[20:23], v[148:151], v[202:205], v[20:23]
	v_mfma_f32_16x16x32_bf16 v[16:19], v[174:177], v[202:205], v[16:19]
	v_mfma_f32_16x16x32_bf16 v[4:7], v[148:151], v[216:219], v[4:7]
	v_mfma_f32_16x16x32_bf16 v[0:3], v[174:177], v[216:219], v[0:3]
	v_mfma_f32_16x16x32_bf16 v[52:55], v[164:167], v[186:189], v[52:55]
	v_mfma_f32_16x16x32_bf16 v[48:51], v[178:181], v[186:189], v[48:51]
	v_mfma_f32_16x16x32_bf16 v[36:39], v[164:167], v[198:201], v[36:39]
	v_mfma_f32_16x16x32_bf16 v[32:35], v[178:181], v[198:201], v[32:35]
	v_mfma_f32_16x16x32_bf16 v[20:23], v[164:167], v[206:209], v[20:23]
	v_mfma_f32_16x16x32_bf16 v[16:19], v[178:181], v[206:209], v[16:19]
	v_mfma_f32_16x16x32_bf16 v[4:7], v[164:167], v[220:223], v[4:7]
	v_mfma_f32_16x16x32_bf16 v[0:3], v[178:181], v[220:223], v[0:3]
	s_setprio 0
	s_barrier
	s_add_i32 s48, s48, 2
	s_add_u32 s8, s8, 0x100
	s_addc_u32 s9, s9, 0
	s_cmp_gt_u32 s48, 29
	s_cbranch_scc0 .LBB0_128
	s_and_b64 vcc, exec, s[12:13]
	s_cbranch_vccz .LBB0_131
	s_barrier

; #define STAGE_A(bufoff, gbase) STAGEX(bufoff, gbase, voffA)
; #define STAGE_B(bufoff, gbase) STAGEX(bufoff, gbase, voffB)
; #define LDA(dst, b, h) do { _Pragma("unroll") for (int m = 0; m < 4; ++m) _Pragma("unroll") for (int k = 0; k < 2; ++k) dst[m][k] = *(const __attribute__((address_space(3))) bf16x8*)(lds + SA(b, h) + aoff + m * 2048 + k * 1024); } while (0)
; #define LDB(dst, b, h) do { _Pragma("unroll") for (int n = 0; n < 2; ++n) _Pragma("unroll") for (int k = 0; k < 2; ++k) dst[n][k] = *(const __attribute__((address_space(3))) bf16x8*)(lds + SB_(b, h) + boff + n * 2048 + k * 1024); } while (0)
; #define MMA(ai, bj, At, Bt_) do { __builtin_amdgcn_s_setprio(1); _Pragma("unroll") for (int m = 0; m < 4; ++m) _Pragma("unroll") for (int n = 0; n < 2; ++n) _Pragma("unroll") for (int k = 0; k < 2; ++k) \
;       acc[ai][bj][m][n] = __builtin_amdgcn_mfma_f32_16x16x32_bf16(Bt_[n][k], At[m][k], acc[ai][bj][m][n], 0, 0, 0); \
;     __builtin_amdgcn_s_setprio(0); } while (0)
; #define WAIT_V(n) asm volatile("s_waitcnt vmcnt(" #n ")" ::: "memory")
; #define BAR __builtin_amdgcn_s_barrier()
; template <int MODE>
; DEV void gemm_phase(const bf16_t* __restrict__ A, const bf16_t* __restrict__ Bt, int M, int N, int K, bf16_t* __restrict__ Out, int ldo,
;                     const float* __restrict__ rstd, const float* __restrict__ rope) {
;     ...
;     for (int t = 0; t < nt; t += 2) {
;       const bool last = (t == nt - 2);
;       const char* a1 = cA + (size_t)(t + 1) * 128;
;       const char* a2 = last ? nA : cA + (size_t)(t + 2) * 128; const char* b2 = last ? nB : cB + (size_t)(t + 2) * 128;
;       const char* a3 = a2 + 128; const char* b3 = b2 + 128;
;       LDB(B0, 0, 0); LDB(B1, 0, 1); SCHED; LDA(At, 0, 0); STAGE_A(SA(1, 1), a1 + hstep);
;       WAIT_V(8); WAIT_L(0); BAR; MMA(0, 0, At, B0); MMA(0, 1, At, B1); BAR; SCHED;
;       LDA(At, 0, 1); STAGE_B(SB_(0, 0), b2); STAGE_B(SB_(0, 1), b2 + hstep); STAGE_A(SA(0, 0), a2);
;       WAIT_V(8); WAIT_L(0); BAR; MMA(1, 0, At, B0); MMA(1, 1, At, B1); BAR; SCHED;
;       LDB(B0, 1, 0); LDB(B1, 1, 1); SCHED; LDA(At, 1, 0); STAGE_A(SA(0, 1), a2 + hstep);
;       WAIT_V(8); WAIT_L(0); BAR; MMA(0, 0, At, B0); MMA(0, 1, At, B1); BAR; SCHED;
;       LDA(At, 1, 1); STAGE_B(SB_(1, 0), b3); STAGE_B(SB_(1, 1), b3 + hstep); STAGE_A(SA(1, 0), a3);
;       WAIT_V(8); WAIT_L(0); BAR; MMA(1, 0, At, B0); MMA(1, 1, At, B1); BAR; SCHED;
.LBB0_493:
	s_add_u32 s20, s18, 0xfff80080
	s_addc_u32 s21, s19, -1
	s_add_i32 s39, 0, 0x10000
	s_cmp_eq_u32 s38, 28
	s_cselect_b32 s23, s15, s21
	s_cselect_b32 s22, s14, s20
	v_add_u32_e32 v143, s39, v141
	s_cselect_b32 s21, s13, s37
	s_cselect_b32 s20, s11, s36
	s_add_i32 s42, 0, 0x14000
	ds_read_b128 v[144:147], v143
	ds_read_b128 v[148:151], v143 offset:1024
	ds_read_b128 v[152:155], v143 offset:2048
	ds_read_b128 v[156:159], v143 offset:3072
	v_add_u32_e32 v143, s42, v141
	ds_read_b128 v[160:163], v143
	ds_read_b128 v[164:167], v143 offset:1024
	ds_read_b128 v[168:171], v143 offset:2048
	ds_read_b128 v[172:175], v143 offset:3072
	v_lshl_add_u64 v[212:213], s[18:19], 0, v[136:137]
	s_add_i32 m0, s25, 0xc000
	ds_read_b128 v[176:179], v142
	ds_read_b128 v[180:183], v142 offset:1024
	ds_read_b128 v[184:187], v142 offset:2048
	ds_read_b128 v[188:191], v142 offset:3072
	ds_read_b128 v[194:197], v142 offset:4096
	ds_read_b128 v[198:201], v142 offset:5120
	ds_read_b128 v[202:205], v142 offset:6144
	ds_read_b128 v[206:209], v142 offset:7168
	global_load_lds_dwordx4 v[212:213], off
	v_lshl_add_u64 v[212:213], s[18:19], 0, v[138:139]
	s_add_i32 m0, s25, 0xe000
	s_nop 0
	global_load_lds_dwordx4 v[212:213], off
	s_waitcnt vmcnt(8)
	s_waitcnt lgkmcnt(0)
	s_setprio 1
	s_barrier
	v_mfma_f32_16x16x32_bf16 v[124:127], v[144:147], v[176:179], v[124:127]
	v_mfma_f32_16x16x32_bf16 v[120:123], v[152:155], v[176:179], v[120:123]
	v_mfma_f32_16x16x32_bf16 v[116:119], v[144:147], v[184:187], v[116:119]
	v_mfma_f32_16x16x32_bf16 v[112:115], v[152:155], v[184:187], v[112:115]
	v_mfma_f32_16x16x32_bf16 v[100:103], v[144:147], v[194:197], v[100:103]
	v_mfma_f32_16x16x32_bf16 v[96:99], v[152:155], v[194:197], v[96:99]
	v_mfma_f32_16x16x32_bf16 v[84:87], v[144:147], v[202:205], v[84:87]
	v_mfma_f32_16x16x32_bf16 v[80:83], v[152:155], v[202:205], v[80:83]
	v_mfma_f32_16x16x32_bf16 v[124:127], v[148:151], v[180:183], v[124:127]
	v_mfma_f32_16x16x32_bf16 v[120:123], v[156:159], v[180:183], v[120:123]
	v_mfma_f32_16x16x32_bf16 v[116:119], v[148:151], v[188:191], v[116:119]
	v_mfma_f32_16x16x32_bf16 v[112:115], v[156:159], v[188:191], v[112:115]
	v_mfma_f32_16x16x32_bf16 v[100:103], v[148:151], v[198:201], v[100:103]
	v_mfma_f32_16x16x32_bf16 v[96:99], v[156:159], v[198:201], v[96:99]
	v_mfma_f32_16x16x32_bf16 v[84:87], v[148:151], v[206:209], v[84:87]
	v_mfma_f32_16x16x32_bf16 v[80:83], v[156:159], v[206:209], v[80:83]
	v_mfma_f32_16x16x32_bf16 v[108:111], v[160:163], v[176:179], v[108:111]
	v_mfma_f32_16x16x32_bf16 v[104:107], v[168:171], v[176:179], v[104:107]
	v_mfma_f32_16x16x32_bf16 v[92:95], v[160:163], v[184:187], v[92:95]
	v_mfma_f32_16x16x32_bf16 v[88:91], v[168:171], v[184:187], v[88:91]
	v_mfma_f32_16x16x32_bf16 v[76:79], v[160:163], v[194:197], v[76:79]
	v_mfma_f32_16x16x32_bf16 v[72:75], v[168:171], v[194:197], v[72:75]
	v_mfma_f32_16x16x32_bf16 v[68:71], v[160:163], v[202:205], v[68:71]
	v_mfma_f32_16x16x32_bf16 v[64:67], v[168:171], v[202:205], v[64:67]
	v_mfma_f32_16x16x32_bf16 v[108:111], v[164:167], v[180:183], v[108:111]
	v_mfma_f32_16x16x32_bf16 v[104:107], v[172:175], v[180:183], v[104:107]
	v_mfma_f32_16x16x32_bf16 v[92:95], v[164:167], v[188:191], v[92:95]
	v_mfma_f32_16x16x32_bf16 v[88:91], v[172:175], v[188:191], v[88:91]
	v_mfma_f32_16x16x32_bf16 v[76:79], v[164:167], v[198:201], v[76:79]
	v_mfma_f32_16x16x32_bf16 v[72:75], v[172:175], v[198:201], v[72:75]
	v_mfma_f32_16x16x32_bf16 v[68:71], v[164:167], v[206:209], v[68:71]
	v_mfma_f32_16x16x32_bf16 v[64:67], v[172:175], v[206:209], v[64:67]
	s_setprio 0
	s_barrier
	s_add_i32 s39, s39, s24
	v_lshl_add_u64 v[212:213], s[20:21], 0, v[192:193]
	s_mov_b32 m0, s39
	ds_read_b128 v[176:179], v142 offset:16384
	ds_read_b128 v[180:183], v142 offset:17408
	ds_read_b128 v[184:187], v142 offset:18432
	ds_read_b128 v[188:191], v142 offset:19456
	ds_read_b128 v[194:197], v142 offset:20480
	ds_read_b128 v[198:201], v142 offset:21504
	ds_read_b128 v[202:205], v142 offset:22528
	ds_read_b128 v[206:209], v142 offset:23552
	global_load_lds_dwordx4 v[212:213], off
	s_add_i32 m0, s39, 0x2000
	s_add_u32 s40, s20, 0x80000
	v_lshl_add_u64 v[214:215], s[20:21], 0, v[128:129]
	s_addc_u32 s41, s21, 0
	s_add_i32 s39, s42, s24
	global_load_lds_dwordx4 v[214:215], off
	v_lshl_add_u64 v[222:223], s[40:41], 0, v[192:193]
	s_mov_b32 m0, s39
	v_lshl_add_u64 v[224:225], s[22:23], 0, v[130:131]
	global_load_lds_dwordx4 v[222:223], off
	v_lshl_add_u64 v[222:223], s[40:41], 0, v[128:129]
	s_add_i32 m0, s39, 0x2000
	s_nop 0
	global_load_lds_dwordx4 v[222:223], off
	v_lshl_add_u64 v[222:223], s[22:23], 0, v[132:133]
	s_mov_b32 m0, s25
	s_nop 0
	global_load_lds_dwordx4 v[222:223], off
	s_mov_b32 m0, s26
	s_nop 0
	global_load_lds_dwordx4 v[224:225], off
	s_waitcnt vmcnt(8)
	s_waitcnt lgkmcnt(0)
	s_setprio 1
	s_barrier
; #define STAGE_A(bufoff, gbase) STAGEX(bufoff, gbase, voffA)
; #define STAGE_B(bufoff, gbase) STAGEX(bufoff, gbase, voffB)
; #define LDA(dst, b, h) do { _Pragma("unroll") for (int m = 0; m < 4; ++m) _Pragma("unroll") for (int k = 0; k < 2; ++k) dst[m][k] = *(const __attribute__((address_space(3))) bf16x8*)(lds + SA(b, h) + aoff + m * 2048 + k * 1024); } while (0)
; #define LDB(dst, b, h) do { _Pragma("unroll") for (int n = 0; n < 2; ++n) _Pragma("unroll") for (int k = 0; k < 2; ++k) dst[n][k] = *(const __attribute__((address_space(3))) bf16x8*)(lds + SB_(b, h) + boff + n * 2048 + k * 1024); } while (0)
; #define MMA(ai, bj, At, Bt_) do { __builtin_amdgcn_s_setprio(1); _Pragma("unroll") for (int m = 0; m < 4; ++m) _Pragma("unroll") for (int n = 0; n < 2; ++n) _Pragma("unroll") for (int k = 0; k < 2; ++k) \
;       acc[ai][bj][m][n] = __builtin_amdgcn_mfma_f32_16x16x32_bf16(Bt_[n][k], At[m][k], acc[ai][bj][m][n], 0, 0, 0); \
;     __builtin_amdgcn_s_setprio(0); } while (0)
; #define WAIT_V(n) asm volatile("s_waitcnt vmcnt(" #n ")" ::: "memory")
; #define BAR __builtin_amdgcn_s_barrier()
; template <int MODE>
; DEV void gemm_phase(const bf16_t* __restrict__ A, const bf16_t* __restrict__ Bt, int M, int N, int K, bf16_t* __restrict__ Out, int ldo,
;                     const float* __restrict__ rstd, const float* __restrict__ rope) {
;     ...
;     for (int t = 0; t < nt; t += 2) {
;       const bool last = (t == nt - 2);
;       const char* a1 = cA + (size_t)(t + 1) * 128;
;       const char* a2 = last ? nA : cA + (size_t)(t + 2) * 128; const char* b2 = last ? nB : cB + (size_t)(t + 2) * 128;
;       const char* a3 = a2 + 128; const char* b3 = b2 + 128;
;       LDB(B0, 0, 0); LDB(B1, 0, 1); SCHED; LDA(At, 0, 0); STAGE_A(SA(1, 1), a1 + hstep);
;       WAIT_V(8); WAIT_L(0); BAR; MMA(0, 0, At, B0); MMA(0, 1, At, B1); BAR; SCHED;
;       LDA(At, 0, 1); STAGE_B(SB_(0, 0), b2); STAGE_B(SB_(0, 1), b2 + hstep); STAGE_A(SA(0, 0), a2);
;       WAIT_V(8); WAIT_L(0); BAR; MMA(1, 0, At, B0); MMA(1, 1, At, B1); BAR; SCHED;
;       LDB(B0, 1, 0); LDB(B1, 1, 1); SCHED; LDA(At, 1, 0); STAGE_A(SA(0, 1), a2 + hstep);
;       WAIT_V(8); WAIT_L(0); BAR; MMA(0, 0, At, B0); MMA(0, 1, At, B1); BAR; SCHED;
;       LDA(At, 1, 1); STAGE_B(SB_(1, 0), b3); STAGE_B(SB_(1, 1), b3 + hstep); STAGE_A(SA(1, 0), a3);
;       WAIT_V(8); WAIT_L(0); BAR; MMA(1, 0, At, B0); MMA(1, 1, At, B1); BAR; SCHED;
	v_mfma_f32_16x16x32_bf16 v[60:63], v[144:147], v[176:179], v[60:63]
	v_mfma_f32_16x16x32_bf16 v[56:59], v[152:155], v[176:179], v[56:59]
	v_mfma_f32_16x16x32_bf16 v[52:55], v[144:147], v[184:187], v[52:55]
	v_mfma_f32_16x16x32_bf16 v[48:51], v[152:155], v[184:187], v[48:51]
	v_mfma_f32_16x16x32_bf16 v[36:39], v[144:147], v[194:197], v[36:39]
	v_mfma_f32_16x16x32_bf16 v[32:35], v[152:155], v[194:197], v[32:35]
	v_mfma_f32_16x16x32_bf16 v[20:23], v[144:147], v[202:205], v[20:23]
	v_mfma_f32_16x16x32_bf16 v[16:19], v[152:155], v[202:205], v[16:19]
	v_mfma_f32_16x16x32_bf16 v[60:63], v[148:151], v[180:183], v[60:63]
	v_mfma_f32_16x16x32_bf16 v[56:59], v[156:159], v[180:183], v[56:59]
	v_mfma_f32_16x16x32_bf16 v[52:55], v[148:151], v[188:191], v[52:55]
	v_mfma_f32_16x16x32_bf16 v[48:51], v[156:159], v[188:191], v[48:51]
	v_mfma_f32_16x16x32_bf16 v[36:39], v[148:151], v[198:201], v[36:39]
	v_mfma_f32_16x16x32_bf16 v[32:35], v[156:159], v[198:201], v[32:35]
	v_mfma_f32_16x16x32_bf16 v[20:23], v[148:151], v[206:209], v[20:23]
	v_mfma_f32_16x16x32_bf16 v[16:19], v[156:159], v[206:209], v[16:19]
	v_mfma_f32_16x16x32_bf16 v[44:47], v[160:163], v[176:179], v[44:47]
	v_mfma_f32_16x16x32_bf16 v[40:43], v[168:171], v[176:179], v[40:43]
	v_mfma_f32_16x16x32_bf16 v[28:31], v[160:163], v[184:187], v[28:31]
	v_mfma_f32_16x16x32_bf16 v[24:27], v[168:171], v[184:187], v[24:27]
	v_mfma_f32_16x16x32_bf16 v[12:15], v[160:163], v[194:197], v[12:15]
	v_mfma_f32_16x16x32_bf16 v[8:11], v[168:171], v[194:197], v[8:11]
	v_mfma_f32_16x16x32_bf16 v[4:7], v[160:163], v[202:205], v[4:7]
	v_mfma_f32_16x16x32_bf16 v[0:3], v[168:171], v[202:205], v[0:3]
	v_mfma_f32_16x16x32_bf16 v[44:47], v[164:167], v[180:183], v[44:47]
	v_mfma_f32_16x16x32_bf16 v[40:43], v[172:175], v[180:183], v[40:43]
	v_mfma_f32_16x16x32_bf16 v[28:31], v[164:167], v[188:191], v[28:31]
	v_mfma_f32_16x16x32_bf16 v[24:27], v[172:175], v[188:191], v[24:27]
	v_mfma_f32_16x16x32_bf16 v[12:15], v[164:167], v[198:201], v[12:15]
	v_mfma_f32_16x16x32_bf16 v[8:11], v[172:175], v[198:201], v[8:11]
	v_mfma_f32_16x16x32_bf16 v[4:7], v[164:167], v[206:209], v[4:7]
	v_mfma_f32_16x16x32_bf16 v[0:3], v[172:175], v[206:209], v[0:3]
	s_setprio 0
	s_barrier
	s_add_i32 s39, 0, 0x18000
	v_add_u32_e32 v143, s39, v141
	s_add_i32 s40, 0, 0x1c000
	ds_read_b128 v[144:147], v143
	ds_read_b128 v[148:151], v143 offset:1024
	ds_read_b128 v[152:155], v143 offset:2048
	ds_read_b128 v[156:159], v143 offset:3072
	v_add_u32_e32 v143, s40, v141
	ds_read_b128 v[160:163], v143
	ds_read_b128 v[164:167], v143 offset:1024
	ds_read_b128 v[168:171], v143 offset:2048
	ds_read_b128 v[172:175], v143 offset:3072
	s_add_u32 s22, s22, 0x80000
	s_addc_u32 s23, s23, 0
	s_mov_b32 m0, s27
	v_lshl_add_u64 v[226:227], s[22:23], 0, v[132:133]
	ds_read_b128 v[176:179], v142 offset:32768
	ds_read_b128 v[180:183], v142 offset:33792
	ds_read_b128 v[184:187], v142 offset:34816
	ds_read_b128 v[188:191], v142 offset:35840
	ds_read_b128 v[194:197], v142 offset:36864
	ds_read_b128 v[198:201], v142 offset:37888
	ds_read_b128 v[202:205], v142 offset:38912
	ds_read_b128 v[206:209], v142 offset:39936
	global_load_lds_dwordx4 v[226:227], off
	v_lshl_add_u64 v[226:227], s[22:23], 0, v[130:131]
	s_mov_b32 m0, s28
	s_nop 0
	global_load_lds_dwordx4 v[226:227], off
	s_waitcnt vmcnt(8)
	s_waitcnt lgkmcnt(0)
	s_setprio 1
	s_barrier
	v_mfma_f32_16x16x32_bf16 v[124:127], v[144:147], v[176:179], v[124:127]
	v_mfma_f32_16x16x32_bf16 v[120:123], v[152:155], v[176:179], v[120:123]
	v_mfma_f32_16x16x32_bf16 v[116:119], v[144:147], v[184:187], v[116:119]
	v_mfma_f32_16x16x32_bf16 v[112:115], v[152:155], v[184:187], v[112:115]
	v_mfma_f32_16x16x32_bf16 v[100:103], v[144:147], v[194:197], v[100:103]
	v_mfma_f32_16x16x32_bf16 v[96:99], v[152:155], v[194:197], v[96:99]
	v_mfma_f32_16x16x32_bf16 v[84:87], v[144:147], v[202:205], v[84:87]
	v_mfma_f32_16x16x32_bf16 v[80:83], v[152:155], v[202:205], v[80:83]
	v_mfma_f32_16x16x32_bf16 v[124:127], v[148:151], v[180:183], v[124:127]
	v_mfma_f32_16x16x32_bf16 v[120:123], v[156:159], v[180:183], v[120:123]
	v_mfma_f32_16x16x32_bf16 v[116:119], v[148:151], v[188:191], v[116:119]
	v_mfma_f32_16x16x32_bf16 v[112:115], v[156:159], v[188:191], v[112:115]
	v_mfma_f32_16x16x32_bf16 v[100:103], v[148:151], v[198:201], v[100:103]
	v_mfma_f32_16x16x32_bf16 v[96:99], v[156:159], v[198:201], v[96:99]
	v_mfma_f32_16x16x32_bf16 v[84:87], v[148:151], v[206:209], v[84:87]
	v_mfma_f32_16x16x32_bf16 v[80:83], v[156:159], v[206:209], v[80:83]
	v_mfma_f32_16x16x32_bf16 v[108:111], v[160:163], v[176:179], v[108:111]
	v_mfma_f32_16x16x32_bf16 v[104:107], v[168:171], v[176:179], v[104:107]
	v_mfma_f32_16x16x32_bf16 v[92:95], v[160:163], v[184:187], v[92:95]
	v_mfma_f32_16x16x32_bf16 v[88:91], v[168:171], v[184:187], v[88:91]
	v_mfma_f32_16x16x32_bf16 v[76:79], v[160:163], v[194:197], v[76:79]
	v_mfma_f32_16x16x32_bf16 v[72:75], v[168:171], v[194:197], v[72:75]
	v_mfma_f32_16x16x32_bf16 v[68:71], v[160:163], v[202:205], v[68:71]
	v_mfma_f32_16x16x32_bf16 v[64:67], v[168:171], v[202:205], v[64:67]
	v_mfma_f32_16x16x32_bf16 v[108:111], v[164:167], v[180:183], v[108:111]
	v_mfma_f32_16x16x32_bf16 v[104:107], v[172:175], v[180:183], v[104:107]
	v_mfma_f32_16x16x32_bf16 v[92:95], v[164:167], v[188:191], v[92:95]
	v_mfma_f32_16x16x32_bf16 v[88:91], v[172:175], v[188:191], v[88:91]
	v_mfma_f32_16x16x32_bf16 v[76:79], v[164:167], v[198:201], v[76:79]
	v_mfma_f32_16x16x32_bf16 v[72:75], v[172:175], v[198:201], v[72:75]
	v_mfma_f32_16x16x32_bf16 v[68:71], v[164:167], v[206:209], v[68:71]
	v_mfma_f32_16x16x32_bf16 v[64:67], v[172:175], v[206:209], v[64:67]
	s_setprio 0
	s_barrier
; #define STAGE_A(bufoff, gbase) STAGEX(bufoff, gbase, voffA)
; #define STAGE_B(bufoff, gbase) STAGEX(bufoff, gbase, voffB)
; #define LDA(dst, b, h) do { _Pragma("unroll") for (int m = 0; m < 4; ++m) _Pragma("unroll") for (int k = 0; k < 2; ++k) dst[m][k] = *(const __attribute__((address_space(3))) bf16x8*)(lds + SA(b, h) + aoff + m * 2048 + k * 1024); } while (0)
; #define LDB(dst, b, h) do { _Pragma("unroll") for (int n = 0; n < 2; ++n) _Pragma("unroll") for (int k = 0; k < 2; ++k) dst[n][k] = *(const __attribute__((address_space(3))) bf16x8*)(lds + SB_(b, h) + boff + n * 2048 + k * 1024); } while (0)
; #define MMA(ai, bj, At, Bt_) do { __builtin_amdgcn_s_setprio(1); _Pragma("unroll") for (int m = 0; m < 4; ++m) _Pragma("unroll") for (int n = 0; n < 2; ++n) _Pragma("unroll") for (int k = 0; k < 2; ++k) \
;       acc[ai][bj][m][n] = __builtin_amdgcn_mfma_f32_16x16x32_bf16(Bt_[n][k], At[m][k], acc[ai][bj][m][n], 0, 0, 0); \
;     __builtin_amdgcn_s_setprio(0); } while (0)
; #define WAIT_V(n) asm volatile("s_waitcnt vmcnt(" #n ")" ::: "memory")
; #define BAR __builtin_amdgcn_s_barrier()
; template <int MODE>
; DEV void gemm_phase(const bf16_t* __restrict__ A, const bf16_t* __restrict__ Bt, int M, int N, int K, bf16_t* __restrict__ Out, int ldo,
;                     const float* __restrict__ rstd, const float* __restrict__ rope) {
;     ...
;     for (int t = 0; t < nt; t += 2) {
;       const bool last = (t == nt - 2);
;       const char* a1 = cA + (size_t)(t + 1) * 128;
;       const char* a2 = last ? nA : cA + (size_t)(t + 2) * 128; const char* b2 = last ? nB : cB + (size_t)(t + 2) * 128;
;       const char* a3 = a2 + 128; const char* b3 = b2 + 128;
;       LDB(B0, 0, 0); LDB(B1, 0, 1); SCHED; LDA(At, 0, 0); STAGE_A(SA(1, 1), a1 + hstep);
;       WAIT_V(8); WAIT_L(0); BAR; MMA(0, 0, At, B0); MMA(0, 1, At, B1); BAR; SCHED;
;       LDA(At, 0, 1); STAGE_B(SB_(0, 0), b2); STAGE_B(SB_(0, 1), b2 + hstep); STAGE_A(SA(0, 0), a2);
;       WAIT_V(8); WAIT_L(0); BAR; MMA(1, 0, At, B0); MMA(1, 1, At, B1); BAR; SCHED;
;       LDB(B0, 1, 0); LDB(B1, 1, 1); SCHED; LDA(At, 1, 0); STAGE_A(SA(0, 1), a2 + hstep);
;       WAIT_V(8); WAIT_L(0); BAR; MMA(0, 0, At, B0); MMA(0, 1, At, B1); BAR; SCHED;
;       LDA(At, 1, 1); STAGE_B(SB_(1, 0), b3); STAGE_B(SB_(1, 1), b3 + hstep); STAGE_A(SA(1, 0), a3);
;       WAIT_V(8); WAIT_L(0); BAR; MMA(1, 0, At, B0); MMA(1, 1, At, B1); BAR; SCHED;
	s_add_i32 s22, s39, s24
	v_lshl_add_u64 v[212:213], v[212:213], 0, s[44:45]
	s_mov_b32 m0, s22
	ds_read_b128 v[176:179], v142 offset:49152
	ds_read_b128 v[180:183], v142 offset:50176
	ds_read_b128 v[184:187], v142 offset:51200
	ds_read_b128 v[188:191], v142 offset:52224
	ds_read_b128 v[194:197], v142 offset:53248
	ds_read_b128 v[198:201], v142 offset:54272
	ds_read_b128 v[202:205], v142 offset:55296
	ds_read_b128 v[206:209], v142 offset:56320
	global_load_lds_dwordx4 v[212:213], off
	s_add_i32 m0, s22, 0x2000
	s_add_u32 s20, s20, 0x80080
	v_lshl_add_u64 v[212:213], v[214:215], 0, s[44:45]
	s_addc_u32 s21, s21, 0
	s_add_i32 s22, s40, s24
	global_load_lds_dwordx4 v[212:213], off
	v_lshl_add_u64 v[212:213], s[20:21], 0, v[192:193]
	s_mov_b32 m0, s22
	s_nop 0
	global_load_lds_dwordx4 v[212:213], off
	v_lshl_add_u64 v[212:213], s[20:21], 0, v[128:129]
	s_add_i32 m0, s22, 0x2000
	s_nop 0
	global_load_lds_dwordx4 v[212:213], off
	v_lshl_add_u64 v[212:213], v[222:223], 0, s[44:45]
	s_mov_b32 m0, s29
	s_nop 0
	global_load_lds_dwordx4 v[212:213], off
	v_lshl_add_u64 v[212:213], v[224:225], 0, s[44:45]
	s_mov_b32 m0, s30
	s_nop 0
	global_load_lds_dwordx4 v[212:213], off
	s_waitcnt vmcnt(8)
	s_waitcnt lgkmcnt(0)
	s_setprio 1
	s_barrier
	v_mfma_f32_16x16x32_bf16 v[60:63], v[144:147], v[176:179], v[60:63]
	v_mfma_f32_16x16x32_bf16 v[56:59], v[152:155], v[176:179], v[56:59]
	v_mfma_f32_16x16x32_bf16 v[52:55], v[144:147], v[184:187], v[52:55]
	v_mfma_f32_16x16x32_bf16 v[48:51], v[152:155], v[184:187], v[48:51]
	v_mfma_f32_16x16x32_bf16 v[36:39], v[144:147], v[194:197], v[36:39]
	v_mfma_f32_16x16x32_bf16 v[32:35], v[152:155], v[194:197], v[32:35]
	v_mfma_f32_16x16x32_bf16 v[20:23], v[144:147], v[202:205], v[20:23]
	v_mfma_f32_16x16x32_bf16 v[16:19], v[152:155], v[202:205], v[16:19]
	v_mfma_f32_16x16x32_bf16 v[60:63], v[148:151], v[180:183], v[60:63]
	v_mfma_f32_16x16x32_bf16 v[56:59], v[156:159], v[180:183], v[56:59]
	v_mfma_f32_16x16x32_bf16 v[52:55], v[148:151], v[188:191], v[52:55]
	v_mfma_f32_16x16x32_bf16 v[48:51], v[156:159], v[188:191], v[48:51]
	v_mfma_f32_16x16x32_bf16 v[36:39], v[148:151], v[198:201], v[36:39]
	v_mfma_f32_16x16x32_bf16 v[32:35], v[156:159], v[198:201], v[32:35]
	v_mfma_f32_16x16x32_bf16 v[20:23], v[148:151], v[206:209], v[20:23]
	v_mfma_f32_16x16x32_bf16 v[16:19], v[156:159], v[206:209], v[16:19]
	v_mfma_f32_16x16x32_bf16 v[44:47], v[160:163], v[176:179], v[44:47]
	v_mfma_f32_16x16x32_bf16 v[40:43], v[168:171], v[176:179], v[40:43]
	v_mfma_f32_16x16x32_bf16 v[28:31], v[160:163], v[184:187], v[28:31]
	v_mfma_f32_16x16x32_bf16 v[24:27], v[168:171], v[184:187], v[24:27]
	v_mfma_f32_16x16x32_bf16 v[12:15], v[160:163], v[194:197], v[12:15]
	v_mfma_f32_16x16x32_bf16 v[8:11], v[168:171], v[194:197], v[8:11]
	v_mfma_f32_16x16x32_bf16 v[4:7], v[160:163], v[202:205], v[4:7]
	v_mfma_f32_16x16x32_bf16 v[0:3], v[168:171], v[202:205], v[0:3]
	v_mfma_f32_16x16x32_bf16 v[44:47], v[164:167], v[180:183], v[44:47]
	v_mfma_f32_16x16x32_bf16 v[40:43], v[172:175], v[180:183], v[40:43]
	v_mfma_f32_16x16x32_bf16 v[28:31], v[164:167], v[188:191], v[28:31]
	v_mfma_f32_16x16x32_bf16 v[24:27], v[172:175], v[188:191], v[24:27]
	v_mfma_f32_16x16x32_bf16 v[12:15], v[164:167], v[198:201], v[12:15]
	v_mfma_f32_16x16x32_bf16 v[8:11], v[172:175], v[198:201], v[8:11]
	v_mfma_f32_16x16x32_bf16 v[4:7], v[164:167], v[206:209], v[4:7]
	v_mfma_f32_16x16x32_bf16 v[0:3], v[172:175], v[206:209], v[0:3]
	s_setprio 0
	s_barrier
	s_add_i32 s38, s38, 2
	s_add_u32 s18, s18, 0x100
	s_addc_u32 s19, s19, 0
	s_add_u32 s36, s36, 0x100
	s_addc_u32 s37, s37, 0
	s_cmp_gt_u32 s38, 29
	s_cbranch_scc0 .LBB0_493
	s_and_b64 vcc, exec, s[6:7]
	s_cbranch_vccz .LBB0_496
	s_barrier

; #define STAGE_A(bufoff, gbase) STAGEX(bufoff, gbase, voffA)
; #define STAGE_B(bufoff, gbase) STAGEX(bufoff, gbase, voffB)
; #define LDA(dst, b, h) do { _Pragma("unroll") for (int m = 0; m < 4; ++m) _Pragma("unroll") for (int k = 0; k < 2; ++k) dst[m][k] = *(const __attribute__((address_space(3))) bf16x8*)(lds + SA(b, h) + aoff + m * 2048 + k * 1024); } while (0)
; #define LDB(dst, b, h) do { _Pragma("unroll") for (int n = 0; n < 2; ++n) _Pragma("unroll") for (int k = 0; k < 2; ++k) dst[n][k] = *(const __attribute__((address_space(3))) bf16x8*)(lds + SB_(b, h) + boff + n * 2048 + k * 1024); } while (0)
; #define MMA(ai, bj, At, Bt_) do { __builtin_amdgcn_s_setprio(1); _Pragma("unroll") for (int m = 0; m < 4; ++m) _Pragma("unroll") for (int n = 0; n < 2; ++n) _Pragma("unroll") for (int k = 0; k < 2; ++k) \
;       acc[ai][bj][m][n] = __builtin_amdgcn_mfma_f32_16x16x32_bf16(Bt_[n][k], At[m][k], acc[ai][bj][m][n], 0, 0, 0); \
;     __builtin_amdgcn_s_setprio(0); } while (0)
; #define WAIT_V(n) asm volatile("s_waitcnt vmcnt(" #n ")" ::: "memory")
; #define BAR __builtin_amdgcn_s_barrier()
; template <int MODE>
; DEV void gemm_phase(const bf16_t* __restrict__ A, const bf16_t* __restrict__ Bt, int M, int N, int K, bf16_t* __restrict__ Out, int ldo,
;                     const float* __restrict__ rstd, const float* __restrict__ rope) {
;     ...
;     for (int t = 0; t < nt; t += 2) {
;       const bool last = (t == nt - 2);
;       const char* a1 = cA + (size_t)(t + 1) * 128;
;       const char* a2 = last ? nA : cA + (size_t)(t + 2) * 128; const char* b2 = last ? nB : cB + (size_t)(t + 2) * 128;
;       const char* a3 = a2 + 128; const char* b3 = b2 + 128;
;       LDB(B0, 0, 0); LDB(B1, 0, 1); SCHED; LDA(At, 0, 0); STAGE_A(SA(1, 1), a1 + hstep);
;       WAIT_V(8); WAIT_L(0); BAR; MMA(0, 0, At, B0); MMA(0, 1, At, B1); BAR; SCHED;
;       LDA(At, 0, 1); STAGE_B(SB_(0, 0), b2); STAGE_B(SB_(0, 1), b2 + hstep); STAGE_A(SA(0, 0), a2);
;       WAIT_V(8); WAIT_L(0); BAR; MMA(1, 0, At, B0); MMA(1, 1, At, B1); BAR; SCHED;
;       LDB(B0, 1, 0); LDB(B1, 1, 1); SCHED; LDA(At, 1, 0); STAGE_A(SA(0, 1), a2 + hstep);
;       WAIT_V(8); WAIT_L(0); BAR; MMA(0, 0, At, B0); MMA(0, 1, At, B1); BAR; SCHED;
;       LDA(At, 1, 1); STAGE_B(SB_(1, 0), b3); STAGE_B(SB_(1, 1), b3 + hstep); STAGE_A(SA(1, 0), a3);
;       WAIT_V(8); WAIT_L(0); BAR; MMA(1, 0, At, B0); MMA(1, 1, At, B1); BAR; SCHED;
.LBB0_618:
	s_add_u32 s20, s38, s18
	s_addc_u32 s21, s39, s19
	s_add_u32 s20, s20, 0x12200100
	s_addc_u32 s21, s21, 0
	s_add_u32 s43, s40, s18
	s_addc_u32 s44, s41, s19
	s_add_i32 s45, 0, 0x10000
	s_cmpk_eq_i32 s18, 0xf00
	s_cselect_b32 s23, s36, s21
	s_cselect_b32 s22, s9, s20
	v_add_u32_e32 v147, s45, v145
	s_cselect_b32 s21, s37, s44
	s_cselect_b32 s20, s11, s43
	s_add_i32 s43, 0, 0x14000
	ds_read_b128 v[148:151], v147
	ds_read_b128 v[152:155], v147 offset:1024
	ds_read_b128 v[156:159], v147 offset:2048
	ds_read_b128 v[160:163], v147 offset:3072
	v_add_u32_e32 v147, s43, v145
	ds_read_b128 v[164:167], v147
	ds_read_b128 v[168:171], v147 offset:1024
	ds_read_b128 v[172:175], v147 offset:2048
	ds_read_b128 v[176:179], v147 offset:3072
	v_lshl_add_u64 v[222:223], v[140:141], 0, s[18:19]
	s_add_i32 m0, s25, 0xc000
	ds_read_b128 v[180:183], v146
	ds_read_b128 v[184:187], v146 offset:1024
	ds_read_b128 v[188:191], v146 offset:2048
	ds_read_b128 v[194:197], v146 offset:3072
	ds_read_b128 v[198:201], v146 offset:4096
	ds_read_b128 v[202:205], v146 offset:5120
	ds_read_b128 v[206:209], v146 offset:6144
	ds_read_b128 v[212:215], v146 offset:7168
	global_load_lds_dwordx4 v[222:223], off
	v_lshl_add_u64 v[222:223], v[142:143], 0, s[18:19]
	s_add_i32 m0, s25, 0xe000
	s_nop 0
	global_load_lds_dwordx4 v[222:223], off
	s_waitcnt vmcnt(8)
	s_waitcnt lgkmcnt(0)
	s_setprio 1
	s_barrier
	v_mfma_f32_16x16x32_bf16 v[124:127], v[148:151], v[180:183], v[124:127]
	v_mfma_f32_16x16x32_bf16 v[120:123], v[156:159], v[180:183], v[120:123]
	v_mfma_f32_16x16x32_bf16 v[108:111], v[148:151], v[188:191], v[108:111]
	v_mfma_f32_16x16x32_bf16 v[104:107], v[156:159], v[188:191], v[104:107]
	v_mfma_f32_16x16x32_bf16 v[92:95], v[148:151], v[198:201], v[92:95]
	v_mfma_f32_16x16x32_bf16 v[88:91], v[156:159], v[198:201], v[88:91]
	v_mfma_f32_16x16x32_bf16 v[76:79], v[148:151], v[206:209], v[76:79]
	v_mfma_f32_16x16x32_bf16 v[72:75], v[156:159], v[206:209], v[72:75]
	v_mfma_f32_16x16x32_bf16 v[124:127], v[152:155], v[184:187], v[124:127]
	v_mfma_f32_16x16x32_bf16 v[120:123], v[160:163], v[184:187], v[120:123]
	v_mfma_f32_16x16x32_bf16 v[108:111], v[152:155], v[194:197], v[108:111]
	v_mfma_f32_16x16x32_bf16 v[104:107], v[160:163], v[194:197], v[104:107]
	v_mfma_f32_16x16x32_bf16 v[92:95], v[152:155], v[202:205], v[92:95]
	v_mfma_f32_16x16x32_bf16 v[88:91], v[160:163], v[202:205], v[88:91]
	v_mfma_f32_16x16x32_bf16 v[76:79], v[152:155], v[212:215], v[76:79]
	v_mfma_f32_16x16x32_bf16 v[72:75], v[160:163], v[212:215], v[72:75]
	v_mfma_f32_16x16x32_bf16 v[116:119], v[164:167], v[180:183], v[116:119]
	v_mfma_f32_16x16x32_bf16 v[112:115], v[172:175], v[180:183], v[112:115]
	v_mfma_f32_16x16x32_bf16 v[100:103], v[164:167], v[188:191], v[100:103]
	v_mfma_f32_16x16x32_bf16 v[96:99], v[172:175], v[188:191], v[96:99]
	v_mfma_f32_16x16x32_bf16 v[84:87], v[164:167], v[198:201], v[84:87]
	v_mfma_f32_16x16x32_bf16 v[80:83], v[172:175], v[198:201], v[80:83]
	v_mfma_f32_16x16x32_bf16 v[68:71], v[164:167], v[206:209], v[68:71]
	v_mfma_f32_16x16x32_bf16 v[64:67], v[172:175], v[206:209], v[64:67]
	v_mfma_f32_16x16x32_bf16 v[116:119], v[168:171], v[184:187], v[116:119]
	v_mfma_f32_16x16x32_bf16 v[112:115], v[176:179], v[184:187], v[112:115]
	v_mfma_f32_16x16x32_bf16 v[100:103], v[168:171], v[194:197], v[100:103]
	v_mfma_f32_16x16x32_bf16 v[96:99], v[176:179], v[194:197], v[96:99]
	v_mfma_f32_16x16x32_bf16 v[84:87], v[168:171], v[202:205], v[84:87]
	v_mfma_f32_16x16x32_bf16 v[80:83], v[176:179], v[202:205], v[80:83]
	v_mfma_f32_16x16x32_bf16 v[68:71], v[168:171], v[212:215], v[68:71]
	v_mfma_f32_16x16x32_bf16 v[64:67], v[176:179], v[212:215], v[64:67]
	s_setprio 0
	s_barrier
	s_add_i32 s44, s45, s24
	v_lshl_add_u64 v[222:223], s[20:21], 0, v[192:193]
	s_mov_b32 m0, s44
	ds_read_b128 v[180:183], v146 offset:16384
	ds_read_b128 v[184:187], v146 offset:17408
	ds_read_b128 v[188:191], v146 offset:18432
	ds_read_b128 v[194:197], v146 offset:19456
	ds_read_b128 v[198:201], v146 offset:20480
	ds_read_b128 v[202:205], v146 offset:21504
	ds_read_b128 v[206:209], v146 offset:22528
	ds_read_b128 v[212:215], v146 offset:23552
	global_load_lds_dwordx4 v[222:223], off
	s_add_i32 m0, s44, 0x2000
	s_add_u32 s44, s20, 0x80000
	v_lshl_add_u64 v[224:225], s[20:21], 0, v[128:129]
	s_addc_u32 s45, s21, 0
	s_add_i32 s43, s43, s24
	global_load_lds_dwordx4 v[224:225], off
	v_lshl_add_u64 v[226:227], s[44:45], 0, v[192:193]
	s_mov_b32 m0, s43
	v_lshl_add_u64 v[228:229], s[22:23], 0, v[130:131]
	global_load_lds_dwordx4 v[226:227], off
	v_lshl_add_u64 v[226:227], s[44:45], 0, v[128:129]
	s_add_i32 m0, s43, 0x2000
	s_nop 0
	global_load_lds_dwordx4 v[226:227], off
	v_lshl_add_u64 v[226:227], s[22:23], 0, v[132:133]
	s_mov_b32 m0, s25
	s_nop 0
	global_load_lds_dwordx4 v[226:227], off
	s_mov_b32 m0, s26
	s_nop 0
	global_load_lds_dwordx4 v[228:229], off
	s_waitcnt vmcnt(8)
	s_waitcnt lgkmcnt(0)
	s_setprio 1
	s_barrier
; #define STAGE_A(bufoff, gbase) STAGEX(bufoff, gbase, voffA)
; #define STAGE_B(bufoff, gbase) STAGEX(bufoff, gbase, voffB)
; #define LDA(dst, b, h) do { _Pragma("unroll") for (int m = 0; m < 4; ++m) _Pragma("unroll") for (int k = 0; k < 2; ++k) dst[m][k] = *(const __attribute__((address_space(3))) bf16x8*)(lds + SA(b, h) + aoff + m * 2048 + k * 1024); } while (0)
; #define LDB(dst, b, h) do { _Pragma("unroll") for (int n = 0; n < 2; ++n) _Pragma("unroll") for (int k = 0; k < 2; ++k) dst[n][k] = *(const __attribute__((address_space(3))) bf16x8*)(lds + SB_(b, h) + boff + n * 2048 + k * 1024); } while (0)
; #define MMA(ai, bj, At, Bt_) do { __builtin_amdgcn_s_setprio(1); _Pragma("unroll") for (int m = 0; m < 4; ++m) _Pragma("unroll") for (int n = 0; n < 2; ++n) _Pragma("unroll") for (int k = 0; k < 2; ++k) \
;       acc[ai][bj][m][n] = __builtin_amdgcn_mfma_f32_16x16x32_bf16(Bt_[n][k], At[m][k], acc[ai][bj][m][n], 0, 0, 0); \
;     __builtin_amdgcn_s_setprio(0); } while (0)
; #define WAIT_V(n) asm volatile("s_waitcnt vmcnt(" #n ")" ::: "memory")
; #define BAR __builtin_amdgcn_s_barrier()
; template <int MODE>
; DEV void gemm_phase(const bf16_t* __restrict__ A, const bf16_t* __restrict__ Bt, int M, int N, int K, bf16_t* __restrict__ Out, int ldo,
;                     const float* __restrict__ rstd, const float* __restrict__ rope) {
;     ...
;     for (int t = 0; t < nt; t += 2) {
;       const bool last = (t == nt - 2);
;       const char* a1 = cA + (size_t)(t + 1) * 128;
;       const char* a2 = last ? nA : cA + (size_t)(t + 2) * 128; const char* b2 = last ? nB : cB + (size_t)(t + 2) * 128;
;       const char* a3 = a2 + 128; const char* b3 = b2 + 128;
;       LDB(B0, 0, 0); LDB(B1, 0, 1); SCHED; LDA(At, 0, 0); STAGE_A(SA(1, 1), a1 + hstep);
;       WAIT_V(8); WAIT_L(0); BAR; MMA(0, 0, At, B0); MMA(0, 1, At, B1); BAR; SCHED;
;       LDA(At, 0, 1); STAGE_B(SB_(0, 0), b2); STAGE_B(SB_(0, 1), b2 + hstep); STAGE_A(SA(0, 0), a2);
;       WAIT_V(8); WAIT_L(0); BAR; MMA(1, 0, At, B0); MMA(1, 1, At, B1); BAR; SCHED;
;       LDB(B0, 1, 0); LDB(B1, 1, 1); SCHED; LDA(At, 1, 0); STAGE_A(SA(0, 1), a2 + hstep);
;       WAIT_V(8); WAIT_L(0); BAR; MMA(0, 0, At, B0); MMA(0, 1, At, B1); BAR; SCHED;
;       LDA(At, 1, 1); STAGE_B(SB_(1, 0), b3); STAGE_B(SB_(1, 1), b3 + hstep); STAGE_A(SA(1, 0), a3);
;       WAIT_V(8); WAIT_L(0); BAR; MMA(1, 0, At, B0); MMA(1, 1, At, B1); BAR; SCHED;
	v_mfma_f32_16x16x32_bf16 v[60:63], v[148:151], v[180:183], v[60:63]
	v_mfma_f32_16x16x32_bf16 v[56:59], v[156:159], v[180:183], v[56:59]
	v_mfma_f32_16x16x32_bf16 v[44:47], v[148:151], v[188:191], v[44:47]
	v_mfma_f32_16x16x32_bf16 v[40:43], v[156:159], v[188:191], v[40:43]
	v_mfma_f32_16x16x32_bf16 v[28:31], v[148:151], v[198:201], v[28:31]
	v_mfma_f32_16x16x32_bf16 v[24:27], v[156:159], v[198:201], v[24:27]
	v_mfma_f32_16x16x32_bf16 v[12:15], v[148:151], v[206:209], v[12:15]
	v_mfma_f32_16x16x32_bf16 v[4:7], v[156:159], v[206:209], v[4:7]
	v_mfma_f32_16x16x32_bf16 v[60:63], v[152:155], v[184:187], v[60:63]
	v_mfma_f32_16x16x32_bf16 v[56:59], v[160:163], v[184:187], v[56:59]
	v_mfma_f32_16x16x32_bf16 v[44:47], v[152:155], v[194:197], v[44:47]
	v_mfma_f32_16x16x32_bf16 v[40:43], v[160:163], v[194:197], v[40:43]
	v_mfma_f32_16x16x32_bf16 v[28:31], v[152:155], v[202:205], v[28:31]
	v_mfma_f32_16x16x32_bf16 v[24:27], v[160:163], v[202:205], v[24:27]
	v_mfma_f32_16x16x32_bf16 v[12:15], v[152:155], v[212:215], v[12:15]
	v_mfma_f32_16x16x32_bf16 v[4:7], v[160:163], v[212:215], v[4:7]
	v_mfma_f32_16x16x32_bf16 v[52:55], v[164:167], v[180:183], v[52:55]
	v_mfma_f32_16x16x32_bf16 v[48:51], v[172:175], v[180:183], v[48:51]
	v_mfma_f32_16x16x32_bf16 v[36:39], v[164:167], v[188:191], v[36:39]
	v_mfma_f32_16x16x32_bf16 v[32:35], v[172:175], v[188:191], v[32:35]
	v_mfma_f32_16x16x32_bf16 v[20:23], v[164:167], v[198:201], v[20:23]
	v_mfma_f32_16x16x32_bf16 v[16:19], v[172:175], v[198:201], v[16:19]
	v_mfma_f32_16x16x32_bf16 v[8:11], v[164:167], v[206:209], v[8:11]
	v_mfma_f32_16x16x32_bf16 v[0:3], v[172:175], v[206:209], v[0:3]
	v_mfma_f32_16x16x32_bf16 v[52:55], v[168:171], v[184:187], v[52:55]
	v_mfma_f32_16x16x32_bf16 v[48:51], v[176:179], v[184:187], v[48:51]
	v_mfma_f32_16x16x32_bf16 v[36:39], v[168:171], v[194:197], v[36:39]
	v_mfma_f32_16x16x32_bf16 v[32:35], v[176:179], v[194:197], v[32:35]
	v_mfma_f32_16x16x32_bf16 v[20:23], v[168:171], v[202:205], v[20:23]
	v_mfma_f32_16x16x32_bf16 v[16:19], v[176:179], v[202:205], v[16:19]
	v_mfma_f32_16x16x32_bf16 v[8:11], v[168:171], v[212:215], v[8:11]
	v_mfma_f32_16x16x32_bf16 v[0:3], v[176:179], v[212:215], v[0:3]
	s_setprio 0
	s_barrier
	s_add_i32 s43, 0, 0x18000
	v_add_u32_e32 v147, s43, v145
	s_add_i32 s44, 0, 0x1c000
	ds_read_b128 v[148:151], v147
	ds_read_b128 v[152:155], v147 offset:1024
	ds_read_b128 v[156:159], v147 offset:2048
	ds_read_b128 v[160:163], v147 offset:3072
	v_add_u32_e32 v147, s44, v145
	ds_read_b128 v[164:167], v147
	ds_read_b128 v[168:171], v147 offset:1024
	ds_read_b128 v[172:175], v147 offset:2048
	ds_read_b128 v[176:179], v147 offset:3072
	s_add_u32 s22, s22, 0x80000
	s_addc_u32 s23, s23, 0
	s_mov_b32 m0, s27
	v_lshl_add_u64 v[230:231], s[22:23], 0, v[132:133]
	ds_read_b128 v[180:183], v146 offset:32768
	ds_read_b128 v[184:187], v146 offset:33792
	ds_read_b128 v[188:191], v146 offset:34816
	ds_read_b128 v[194:197], v146 offset:35840
	ds_read_b128 v[198:201], v146 offset:36864
	ds_read_b128 v[202:205], v146 offset:37888
	ds_read_b128 v[206:209], v146 offset:38912
	ds_read_b128 v[212:215], v146 offset:39936
	global_load_lds_dwordx4 v[230:231], off
	v_lshl_add_u64 v[230:231], s[22:23], 0, v[130:131]
	s_mov_b32 m0, s28
	s_nop 0
	global_load_lds_dwordx4 v[230:231], off
	s_waitcnt vmcnt(8)
	s_waitcnt lgkmcnt(0)
	s_setprio 1
	s_barrier
	v_mfma_f32_16x16x32_bf16 v[124:127], v[148:151], v[180:183], v[124:127]
	v_mfma_f32_16x16x32_bf16 v[120:123], v[156:159], v[180:183], v[120:123]
	v_mfma_f32_16x16x32_bf16 v[108:111], v[148:151], v[188:191], v[108:111]
	v_mfma_f32_16x16x32_bf16 v[104:107], v[156:159], v[188:191], v[104:107]
	v_mfma_f32_16x16x32_bf16 v[92:95], v[148:151], v[198:201], v[92:95]
	v_mfma_f32_16x16x32_bf16 v[88:91], v[156:159], v[198:201], v[88:91]
	v_mfma_f32_16x16x32_bf16 v[76:79], v[148:151], v[206:209], v[76:79]
	v_mfma_f32_16x16x32_bf16 v[72:75], v[156:159], v[206:209], v[72:75]
	v_mfma_f32_16x16x32_bf16 v[124:127], v[152:155], v[184:187], v[124:127]
	v_mfma_f32_16x16x32_bf16 v[120:123], v[160:163], v[184:187], v[120:123]
	v_mfma_f32_16x16x32_bf16 v[108:111], v[152:155], v[194:197], v[108:111]
	v_mfma_f32_16x16x32_bf16 v[104:107], v[160:163], v[194:197], v[104:107]
	v_mfma_f32_16x16x32_bf16 v[92:95], v[152:155], v[202:205], v[92:95]
	v_mfma_f32_16x16x32_bf16 v[88:91], v[160:163], v[202:205], v[88:91]
	v_mfma_f32_16x16x32_bf16 v[76:79], v[152:155], v[212:215], v[76:79]
	v_mfma_f32_16x16x32_bf16 v[72:75], v[160:163], v[212:215], v[72:75]
	v_mfma_f32_16x16x32_bf16 v[116:119], v[164:167], v[180:183], v[116:119]
	v_mfma_f32_16x16x32_bf16 v[112:115], v[172:175], v[180:183], v[112:115]
	v_mfma_f32_16x16x32_bf16 v[100:103], v[164:167], v[188:191], v[100:103]
	v_mfma_f32_16x16x32_bf16 v[96:99], v[172:175], v[188:191], v[96:99]
	v_mfma_f32_16x16x32_bf16 v[84:87], v[164:167], v[198:201], v[84:87]
	v_mfma_f32_16x16x32_bf16 v[80:83], v[172:175], v[198:201], v[80:83]
	v_mfma_f32_16x16x32_bf16 v[68:71], v[164:167], v[206:209], v[68:71]
	v_mfma_f32_16x16x32_bf16 v[64:67], v[172:175], v[206:209], v[64:67]
	v_mfma_f32_16x16x32_bf16 v[116:119], v[168:171], v[184:187], v[116:119]
	v_mfma_f32_16x16x32_bf16 v[112:115], v[176:179], v[184:187], v[112:115]
	v_mfma_f32_16x16x32_bf16 v[100:103], v[168:171], v[194:197], v[100:103]
	v_mfma_f32_16x16x32_bf16 v[96:99], v[176:179], v[194:197], v[96:99]
	v_mfma_f32_16x16x32_bf16 v[84:87], v[168:171], v[202:205], v[84:87]
	v_mfma_f32_16x16x32_bf16 v[80:83], v[176:179], v[202:205], v[80:83]
	v_mfma_f32_16x16x32_bf16 v[68:71], v[168:171], v[212:215], v[68:71]
	v_mfma_f32_16x16x32_bf16 v[64:67], v[176:179], v[212:215], v[64:67]
	s_setprio 0
	s_barrier
; #define STAGE_A(bufoff, gbase) STAGEX(bufoff, gbase, voffA)
; #define STAGE_B(bufoff, gbase) STAGEX(bufoff, gbase, voffB)
; #define LDA(dst, b, h) do { _Pragma("unroll") for (int m = 0; m < 4; ++m) _Pragma("unroll") for (int k = 0; k < 2; ++k) dst[m][k] = *(const __attribute__((address_space(3))) bf16x8*)(lds + SA(b, h) + aoff + m * 2048 + k * 1024); } while (0)
; #define LDB(dst, b, h) do { _Pragma("unroll") for (int n = 0; n < 2; ++n) _Pragma("unroll") for (int k = 0; k < 2; ++k) dst[n][k] = *(const __attribute__((address_space(3))) bf16x8*)(lds + SB_(b, h) + boff + n * 2048 + k * 1024); } while (0)
; #define MMA(ai, bj, At, Bt_) do { __builtin_amdgcn_s_setprio(1); _Pragma("unroll") for (int m = 0; m < 4; ++m) _Pragma("unroll") for (int n = 0; n < 2; ++n) _Pragma("unroll") for (int k = 0; k < 2; ++k) \
;       acc[ai][bj][m][n] = __builtin_amdgcn_mfma_f32_16x16x32_bf16(Bt_[n][k], At[m][k], acc[ai][bj][m][n], 0, 0, 0); \
;     __builtin_amdgcn_s_setprio(0); } while (0)
; #define WAIT_V(n) asm volatile("s_waitcnt vmcnt(" #n ")" ::: "memory")
; #define BAR __builtin_amdgcn_s_barrier()
; template <int MODE>
; DEV void gemm_phase(const bf16_t* __restrict__ A, const bf16_t* __restrict__ Bt, int M, int N, int K, bf16_t* __restrict__ Out, int ldo,
;                     const float* __restrict__ rstd, const float* __restrict__ rope) {
;     ...
;     for (int t = 0; t < nt; t += 2) {
;       const bool last = (t == nt - 2);
;       const char* a1 = cA + (size_t)(t + 1) * 128;
;       const char* a2 = last ? nA : cA + (size_t)(t + 2) * 128; const char* b2 = last ? nB : cB + (size_t)(t + 2) * 128;
;       const char* a3 = a2 + 128; const char* b3 = b2 + 128;
;       LDB(B0, 0, 0); LDB(B1, 0, 1); SCHED; LDA(At, 0, 0); STAGE_A(SA(1, 1), a1 + hstep);
;       WAIT_V(8); WAIT_L(0); BAR; MMA(0, 0, At, B0); MMA(0, 1, At, B1); BAR; SCHED;
;       LDA(At, 0, 1); STAGE_B(SB_(0, 0), b2); STAGE_B(SB_(0, 1), b2 + hstep); STAGE_A(SA(0, 0), a2);
;       WAIT_V(8); WAIT_L(0); BAR; MMA(1, 0, At, B0); MMA(1, 1, At, B1); BAR; SCHED;
;       LDB(B0, 1, 0); LDB(B1, 1, 1); SCHED; LDA(At, 1, 0); STAGE_A(SA(0, 1), a2 + hstep);
;       WAIT_V(8); WAIT_L(0); BAR; MMA(0, 0, At, B0); MMA(0, 1, At, B1); BAR; SCHED;
;       LDA(At, 1, 1); STAGE_B(SB_(1, 0), b3); STAGE_B(SB_(1, 1), b3 + hstep); STAGE_A(SA(1, 0), a3);
;       WAIT_V(8); WAIT_L(0); BAR; MMA(1, 0, At, B0); MMA(1, 1, At, B1); BAR; SCHED;
	s_add_i32 s22, s43, s24
	v_lshl_add_u64 v[222:223], v[222:223], 0, s[46:47]
	s_mov_b32 m0, s22
	ds_read_b128 v[180:183], v146 offset:49152
	ds_read_b128 v[184:187], v146 offset:50176
	ds_read_b128 v[188:191], v146 offset:51200
	ds_read_b128 v[194:197], v146 offset:52224
	ds_read_b128 v[198:201], v146 offset:53248
	ds_read_b128 v[202:205], v146 offset:54272
	ds_read_b128 v[206:209], v146 offset:55296
	ds_read_b128 v[212:215], v146 offset:56320
	global_load_lds_dwordx4 v[222:223], off
	s_add_i32 m0, s22, 0x2000
	s_add_u32 s20, s20, 0x80080
	v_lshl_add_u64 v[222:223], v[224:225], 0, s[46:47]
	s_addc_u32 s21, s21, 0
	s_add_i32 s22, s44, s24
	global_load_lds_dwordx4 v[222:223], off
	v_lshl_add_u64 v[222:223], s[20:21], 0, v[192:193]
	s_mov_b32 m0, s22
	s_nop 0
	global_load_lds_dwordx4 v[222:223], off
	v_lshl_add_u64 v[222:223], s[20:21], 0, v[128:129]
	s_add_i32 m0, s22, 0x2000
	s_nop 0
	global_load_lds_dwordx4 v[222:223], off
	v_lshl_add_u64 v[222:223], v[226:227], 0, s[46:47]
	s_mov_b32 m0, s29
	s_nop 0
	global_load_lds_dwordx4 v[222:223], off
	v_lshl_add_u64 v[222:223], v[228:229], 0, s[46:47]
	s_mov_b32 m0, s30
	s_nop 0
	global_load_lds_dwordx4 v[222:223], off
	s_waitcnt vmcnt(8)
	s_waitcnt lgkmcnt(0)
	s_setprio 1
	s_barrier
	v_mfma_f32_16x16x32_bf16 v[60:63], v[148:151], v[180:183], v[60:63]
	v_mfma_f32_16x16x32_bf16 v[56:59], v[156:159], v[180:183], v[56:59]
	v_mfma_f32_16x16x32_bf16 v[44:47], v[148:151], v[188:191], v[44:47]
	v_mfma_f32_16x16x32_bf16 v[40:43], v[156:159], v[188:191], v[40:43]
	v_mfma_f32_16x16x32_bf16 v[28:31], v[148:151], v[198:201], v[28:31]
	v_mfma_f32_16x16x32_bf16 v[24:27], v[156:159], v[198:201], v[24:27]
	v_mfma_f32_16x16x32_bf16 v[12:15], v[148:151], v[206:209], v[12:15]
	v_mfma_f32_16x16x32_bf16 v[4:7], v[156:159], v[206:209], v[4:7]
	v_mfma_f32_16x16x32_bf16 v[60:63], v[152:155], v[184:187], v[60:63]
	v_mfma_f32_16x16x32_bf16 v[56:59], v[160:163], v[184:187], v[56:59]
	v_mfma_f32_16x16x32_bf16 v[44:47], v[152:155], v[194:197], v[44:47]
	v_mfma_f32_16x16x32_bf16 v[40:43], v[160:163], v[194:197], v[40:43]
	v_mfma_f32_16x16x32_bf16 v[28:31], v[152:155], v[202:205], v[28:31]
	v_mfma_f32_16x16x32_bf16 v[24:27], v[160:163], v[202:205], v[24:27]
	v_mfma_f32_16x16x32_bf16 v[12:15], v[152:155], v[212:215], v[12:15]
	v_mfma_f32_16x16x32_bf16 v[4:7], v[160:163], v[212:215], v[4:7]
	v_mfma_f32_16x16x32_bf16 v[52:55], v[164:167], v[180:183], v[52:55]
	v_mfma_f32_16x16x32_bf16 v[48:51], v[172:175], v[180:183], v[48:51]
	v_mfma_f32_16x16x32_bf16 v[36:39], v[164:167], v[188:191], v[36:39]
	v_mfma_f32_16x16x32_bf16 v[32:35], v[172:175], v[188:191], v[32:35]
	v_mfma_f32_16x16x32_bf16 v[20:23], v[164:167], v[198:201], v[20:23]
	v_mfma_f32_16x16x32_bf16 v[16:19], v[172:175], v[198:201], v[16:19]
	v_mfma_f32_16x16x32_bf16 v[8:11], v[164:167], v[206:209], v[8:11]
	v_mfma_f32_16x16x32_bf16 v[0:3], v[172:175], v[206:209], v[0:3]
	v_mfma_f32_16x16x32_bf16 v[52:55], v[168:171], v[184:187], v[52:55]
	v_mfma_f32_16x16x32_bf16 v[48:51], v[176:179], v[184:187], v[48:51]
	v_mfma_f32_16x16x32_bf16 v[36:39], v[168:171], v[194:197], v[36:39]
	v_mfma_f32_16x16x32_bf16 v[32:35], v[176:179], v[194:197], v[32:35]
	v_mfma_f32_16x16x32_bf16 v[20:23], v[168:171], v[202:205], v[20:23]
	v_mfma_f32_16x16x32_bf16 v[16:19], v[176:179], v[202:205], v[16:19]
	v_mfma_f32_16x16x32_bf16 v[8:11], v[168:171], v[212:215], v[8:11]
	v_mfma_f32_16x16x32_bf16 v[0:3], v[176:179], v[212:215], v[0:3]
	s_setprio 0
	s_barrier
	s_add_i32 s42, s42, 2
	s_add_u32 s18, s18, 0x100
	s_addc_u32 s19, s19, 0
	s_cmp_gt_u32 s42, 29
	s_cbranch_scc0 .LBB0_618
	s_and_b64 vcc, exec, s[6:7]
	s_cbranch_vccz .LBB0_621
	s_barrier

; #define STAGE_A(bufoff, gbase) STAGEX(bufoff, gbase, voffA)
; #define STAGE_B(bufoff, gbase) STAGEX(bufoff, gbase, voffB)
; #define LDA(dst, b, h) do { _Pragma("unroll") for (int m = 0; m < 4; ++m) _Pragma("unroll") for (int k = 0; k < 2; ++k) dst[m][k] = *(const __attribute__((address_space(3))) bf16x8*)(lds + SA(b, h) + aoff + m * 2048 + k * 1024); } while (0)
; #define LDB(dst, b, h) do { _Pragma("unroll") for (int n = 0; n < 2; ++n) _Pragma("unroll") for (int k = 0; k < 2; ++k) dst[n][k] = *(const __attribute__((address_space(3))) bf16x8*)(lds + SB_(b, h) + boff + n * 2048 + k * 1024); } while (0)
; #define MMA(ai, bj, At, Bt_) do { __builtin_amdgcn_s_setprio(1); _Pragma("unroll") for (int m = 0; m < 4; ++m) _Pragma("unroll") for (int n = 0; n < 2; ++n) _Pragma("unroll") for (int k = 0; k < 2; ++k) \
;       acc[ai][bj][m][n] = __builtin_amdgcn_mfma_f32_16x16x32_bf16(Bt_[n][k], At[m][k], acc[ai][bj][m][n], 0, 0, 0); \
;     __builtin_amdgcn_s_setprio(0); } while (0)
; #define WAIT_V(n) asm volatile("s_waitcnt vmcnt(" #n ")" ::: "memory")
; #define BAR __builtin_amdgcn_s_barrier()
; template <int MODE>
; DEV void gemm_phase(const bf16_t* __restrict__ A, const bf16_t* __restrict__ Bt, int M, int N, int K, bf16_t* __restrict__ Out, int ldo,
;                     const float* __restrict__ rstd, const float* __restrict__ rope) {
;     ...
;     for (int t = 0; t < nt; t += 2) {
;       const bool last = (t == nt - 2);
;       const char* a1 = cA + (size_t)(t + 1) * 128;
;       const char* a2 = last ? nA : cA + (size_t)(t + 2) * 128; const char* b2 = last ? nB : cB + (size_t)(t + 2) * 128;
;       const char* a3 = a2 + 128; const char* b3 = b2 + 128;
;       LDB(B0, 0, 0); LDB(B1, 0, 1); SCHED; LDA(At, 0, 0); STAGE_A(SA(1, 1), a1 + hstep);
;       WAIT_V(8); WAIT_L(0); BAR; MMA(0, 0, At, B0); MMA(0, 1, At, B1); BAR; SCHED;
;       LDA(At, 0, 1); STAGE_B(SB_(0, 0), b2); STAGE_B(SB_(0, 1), b2 + hstep); STAGE_A(SA(0, 0), a2);
;       WAIT_V(8); WAIT_L(0); BAR; MMA(1, 0, At, B0); MMA(1, 1, At, B1); BAR; SCHED;
;       LDB(B0, 1, 0); LDB(B1, 1, 1); SCHED; LDA(At, 1, 0); STAGE_A(SA(0, 1), a2 + hstep);
;       WAIT_V(8); WAIT_L(0); BAR; MMA(0, 0, At, B0); MMA(0, 1, At, B1); BAR; SCHED;
;       LDA(At, 1, 1); STAGE_B(SB_(1, 0), b3); STAGE_B(SB_(1, 1), b3 + hstep); STAGE_A(SA(1, 0), a3);
;       WAIT_V(8); WAIT_L(0); BAR; MMA(1, 0, At, B0); MMA(1, 1, At, B1); BAR; SCHED;
.LBB0_690:
	s_add_u32 s14, s12, 0x100
	s_addc_u32 s15, s13, 0
	s_add_i32 s39, 0, 0x10000
	s_cmpk_eq_i32 s38, 0x54
	s_cselect_b32 s19, s9, s15
	s_cselect_b32 s18, s8, s14
	v_add_u32_e32 v143, s39, v141
	s_cselect_b32 s17, s35, s37
	s_cselect_b32 s16, s34, s36
	s_add_i32 s40, 0, 0x14000
	ds_read_b128 v[144:147], v143
	ds_read_b128 v[148:151], v143 offset:1024
	ds_read_b128 v[152:155], v143 offset:2048
	ds_read_b128 v[156:159], v143 offset:3072
	v_add_u32_e32 v143, s40, v141
	ds_read_b128 v[160:163], v143
	ds_read_b128 v[164:167], v143 offset:1024
	ds_read_b128 v[168:171], v143 offset:2048
	ds_read_b128 v[172:175], v143 offset:3072
	v_lshl_add_u64 v[212:213], s[12:13], 0, v[136:137]
	s_add_i32 m0, s21, 0xc000
	ds_read_b128 v[176:179], v142
	ds_read_b128 v[180:183], v142 offset:1024
	ds_read_b128 v[184:187], v142 offset:2048
	ds_read_b128 v[188:191], v142 offset:3072
	ds_read_b128 v[194:197], v142 offset:4096
	ds_read_b128 v[198:201], v142 offset:5120
	ds_read_b128 v[202:205], v142 offset:6144
	ds_read_b128 v[206:209], v142 offset:7168
	global_load_lds_dwordx4 v[212:213], off
	v_lshl_add_u64 v[212:213], s[12:13], 0, v[138:139]
	s_add_i32 m0, s21, 0xe000
	s_nop 0
	global_load_lds_dwordx4 v[212:213], off
	s_waitcnt vmcnt(8)
	s_waitcnt lgkmcnt(0)
	s_setprio 1
	s_barrier
	v_mfma_f32_16x16x32_bf16 v[124:127], v[144:147], v[176:179], v[124:127]
	v_mfma_f32_16x16x32_bf16 v[120:123], v[152:155], v[176:179], v[120:123]
	v_mfma_f32_16x16x32_bf16 v[116:119], v[144:147], v[184:187], v[116:119]
	v_mfma_f32_16x16x32_bf16 v[112:115], v[152:155], v[184:187], v[112:115]
	v_mfma_f32_16x16x32_bf16 v[100:103], v[144:147], v[194:197], v[100:103]
	v_mfma_f32_16x16x32_bf16 v[96:99], v[152:155], v[194:197], v[96:99]
	v_mfma_f32_16x16x32_bf16 v[84:87], v[144:147], v[202:205], v[84:87]
	v_mfma_f32_16x16x32_bf16 v[80:83], v[152:155], v[202:205], v[80:83]
	v_mfma_f32_16x16x32_bf16 v[124:127], v[148:151], v[180:183], v[124:127]
	v_mfma_f32_16x16x32_bf16 v[120:123], v[156:159], v[180:183], v[120:123]
	v_mfma_f32_16x16x32_bf16 v[116:119], v[148:151], v[188:191], v[116:119]
	v_mfma_f32_16x16x32_bf16 v[112:115], v[156:159], v[188:191], v[112:115]
	v_mfma_f32_16x16x32_bf16 v[100:103], v[148:151], v[198:201], v[100:103]
	v_mfma_f32_16x16x32_bf16 v[96:99], v[156:159], v[198:201], v[96:99]
	v_mfma_f32_16x16x32_bf16 v[84:87], v[148:151], v[206:209], v[84:87]
	v_mfma_f32_16x16x32_bf16 v[80:83], v[156:159], v[206:209], v[80:83]
	v_mfma_f32_16x16x32_bf16 v[108:111], v[160:163], v[176:179], v[108:111]
	v_mfma_f32_16x16x32_bf16 v[104:107], v[168:171], v[176:179], v[104:107]
	v_mfma_f32_16x16x32_bf16 v[92:95], v[160:163], v[184:187], v[92:95]
	v_mfma_f32_16x16x32_bf16 v[88:91], v[168:171], v[184:187], v[88:91]
	v_mfma_f32_16x16x32_bf16 v[76:79], v[160:163], v[194:197], v[76:79]
	v_mfma_f32_16x16x32_bf16 v[72:75], v[168:171], v[194:197], v[72:75]
	v_mfma_f32_16x16x32_bf16 v[68:71], v[160:163], v[202:205], v[68:71]
	v_mfma_f32_16x16x32_bf16 v[64:67], v[168:171], v[202:205], v[64:67]
	v_mfma_f32_16x16x32_bf16 v[108:111], v[164:167], v[180:183], v[108:111]
	v_mfma_f32_16x16x32_bf16 v[104:107], v[172:175], v[180:183], v[104:107]
	v_mfma_f32_16x16x32_bf16 v[92:95], v[164:167], v[188:191], v[92:95]
	v_mfma_f32_16x16x32_bf16 v[88:91], v[172:175], v[188:191], v[88:91]
	v_mfma_f32_16x16x32_bf16 v[76:79], v[164:167], v[198:201], v[76:79]
	v_mfma_f32_16x16x32_bf16 v[72:75], v[172:175], v[198:201], v[72:75]
	v_mfma_f32_16x16x32_bf16 v[68:71], v[164:167], v[206:209], v[68:71]
	v_mfma_f32_16x16x32_bf16 v[64:67], v[172:175], v[206:209], v[64:67]
	s_setprio 0
	s_barrier
	s_add_i32 s12, s39, s20
	v_lshl_add_u64 v[212:213], s[16:17], 0, v[192:193]
	s_mov_b32 m0, s12
	ds_read_b128 v[176:179], v142 offset:16384
	ds_read_b128 v[180:183], v142 offset:17408
	ds_read_b128 v[184:187], v142 offset:18432
	ds_read_b128 v[188:191], v142 offset:19456
	ds_read_b128 v[194:197], v142 offset:20480
	ds_read_b128 v[198:201], v142 offset:21504
	ds_read_b128 v[202:205], v142 offset:22528
	ds_read_b128 v[206:209], v142 offset:23552
	global_load_lds_dwordx4 v[212:213], off
	s_add_i32 m0, s12, 0x2000
	s_add_u32 s12, s16, 0x160000
	v_lshl_add_u64 v[214:215], s[16:17], 0, v[128:129]
	s_addc_u32 s13, s17, 0
	s_add_i32 s39, s40, s20
	global_load_lds_dwordx4 v[214:215], off
	v_lshl_add_u64 v[222:223], s[12:13], 0, v[192:193]
	s_mov_b32 m0, s39
	v_lshl_add_u64 v[224:225], s[18:19], 0, v[130:131]
	global_load_lds_dwordx4 v[222:223], off
	v_lshl_add_u64 v[222:223], s[12:13], 0, v[128:129]
	s_add_i32 m0, s39, 0x2000
	s_nop 0
	global_load_lds_dwordx4 v[222:223], off
	v_lshl_add_u64 v[222:223], s[18:19], 0, v[132:133]
	s_mov_b32 m0, s21
	s_nop 0
	global_load_lds_dwordx4 v[222:223], off
	s_mov_b32 m0, s22
	s_nop 0
	global_load_lds_dwordx4 v[224:225], off
	s_waitcnt vmcnt(8)
	s_waitcnt lgkmcnt(0)
	s_setprio 1
	s_barrier
; #define STAGE_A(bufoff, gbase) STAGEX(bufoff, gbase, voffA)
; #define STAGE_B(bufoff, gbase) STAGEX(bufoff, gbase, voffB)
; #define LDA(dst, b, h) do { _Pragma("unroll") for (int m = 0; m < 4; ++m) _Pragma("unroll") for (int k = 0; k < 2; ++k) dst[m][k] = *(const __attribute__((address_space(3))) bf16x8*)(lds + SA(b, h) + aoff + m * 2048 + k * 1024); } while (0)
; #define LDB(dst, b, h) do { _Pragma("unroll") for (int n = 0; n < 2; ++n) _Pragma("unroll") for (int k = 0; k < 2; ++k) dst[n][k] = *(const __attribute__((address_space(3))) bf16x8*)(lds + SB_(b, h) + boff + n * 2048 + k * 1024); } while (0)
; #define MMA(ai, bj, At, Bt_) do { __builtin_amdgcn_s_setprio(1); _Pragma("unroll") for (int m = 0; m < 4; ++m) _Pragma("unroll") for (int n = 0; n < 2; ++n) _Pragma("unroll") for (int k = 0; k < 2; ++k) \
;       acc[ai][bj][m][n] = __builtin_amdgcn_mfma_f32_16x16x32_bf16(Bt_[n][k], At[m][k], acc[ai][bj][m][n], 0, 0, 0); \
;     __builtin_amdgcn_s_setprio(0); } while (0)
; #define WAIT_V(n) asm volatile("s_waitcnt vmcnt(" #n ")" ::: "memory")
; #define BAR __builtin_amdgcn_s_barrier()
; template <int MODE>
; DEV void gemm_phase(const bf16_t* __restrict__ A, const bf16_t* __restrict__ Bt, int M, int N, int K, bf16_t* __restrict__ Out, int ldo,
;                     const float* __restrict__ rstd, const float* __restrict__ rope) {
;     ...
;     for (int t = 0; t < nt; t += 2) {
;       const bool last = (t == nt - 2);
;       const char* a1 = cA + (size_t)(t + 1) * 128;
;       const char* a2 = last ? nA : cA + (size_t)(t + 2) * 128; const char* b2 = last ? nB : cB + (size_t)(t + 2) * 128;
;       const char* a3 = a2 + 128; const char* b3 = b2 + 128;
;       LDB(B0, 0, 0); LDB(B1, 0, 1); SCHED; LDA(At, 0, 0); STAGE_A(SA(1, 1), a1 + hstep);
;       WAIT_V(8); WAIT_L(0); BAR; MMA(0, 0, At, B0); MMA(0, 1, At, B1); BAR; SCHED;
;       LDA(At, 0, 1); STAGE_B(SB_(0, 0), b2); STAGE_B(SB_(0, 1), b2 + hstep); STAGE_A(SA(0, 0), a2);
;       WAIT_V(8); WAIT_L(0); BAR; MMA(1, 0, At, B0); MMA(1, 1, At, B1); BAR; SCHED;
;       LDB(B0, 1, 0); LDB(B1, 1, 1); SCHED; LDA(At, 1, 0); STAGE_A(SA(0, 1), a2 + hstep);
;       WAIT_V(8); WAIT_L(0); BAR; MMA(0, 0, At, B0); MMA(0, 1, At, B1); BAR; SCHED;
;       LDA(At, 1, 1); STAGE_B(SB_(1, 0), b3); STAGE_B(SB_(1, 1), b3 + hstep); STAGE_A(SA(1, 0), a3);
;       WAIT_V(8); WAIT_L(0); BAR; MMA(1, 0, At, B0); MMA(1, 1, At, B1); BAR; SCHED;
	v_mfma_f32_16x16x32_bf16 v[60:63], v[144:147], v[176:179], v[60:63]
	v_mfma_f32_16x16x32_bf16 v[56:59], v[152:155], v[176:179], v[56:59]
	v_mfma_f32_16x16x32_bf16 v[52:55], v[144:147], v[184:187], v[52:55]
	v_mfma_f32_16x16x32_bf16 v[48:51], v[152:155], v[184:187], v[48:51]
	v_mfma_f32_16x16x32_bf16 v[36:39], v[144:147], v[194:197], v[36:39]
	v_mfma_f32_16x16x32_bf16 v[32:35], v[152:155], v[194:197], v[32:35]
	v_mfma_f32_16x16x32_bf16 v[20:23], v[144:147], v[202:205], v[20:23]
	v_mfma_f32_16x16x32_bf16 v[16:19], v[152:155], v[202:205], v[16:19]
	v_mfma_f32_16x16x32_bf16 v[60:63], v[148:151], v[180:183], v[60:63]
	v_mfma_f32_16x16x32_bf16 v[56:59], v[156:159], v[180:183], v[56:59]
	v_mfma_f32_16x16x32_bf16 v[52:55], v[148:151], v[188:191], v[52:55]
	v_mfma_f32_16x16x32_bf16 v[48:51], v[156:159], v[188:191], v[48:51]
	v_mfma_f32_16x16x32_bf16 v[36:39], v[148:151], v[198:201], v[36:39]
	v_mfma_f32_16x16x32_bf16 v[32:35], v[156:159], v[198:201], v[32:35]
	v_mfma_f32_16x16x32_bf16 v[20:23], v[148:151], v[206:209], v[20:23]
	v_mfma_f32_16x16x32_bf16 v[16:19], v[156:159], v[206:209], v[16:19]
	v_mfma_f32_16x16x32_bf16 v[44:47], v[160:163], v[176:179], v[44:47]
	v_mfma_f32_16x16x32_bf16 v[40:43], v[168:171], v[176:179], v[40:43]
	v_mfma_f32_16x16x32_bf16 v[28:31], v[160:163], v[184:187], v[28:31]
	v_mfma_f32_16x16x32_bf16 v[24:27], v[168:171], v[184:187], v[24:27]
	v_mfma_f32_16x16x32_bf16 v[12:15], v[160:163], v[194:197], v[12:15]
	v_mfma_f32_16x16x32_bf16 v[8:11], v[168:171], v[194:197], v[8:11]
	v_mfma_f32_16x16x32_bf16 v[4:7], v[160:163], v[202:205], v[4:7]
	v_mfma_f32_16x16x32_bf16 v[0:3], v[168:171], v[202:205], v[0:3]
	v_mfma_f32_16x16x32_bf16 v[44:47], v[164:167], v[180:183], v[44:47]
	v_mfma_f32_16x16x32_bf16 v[40:43], v[172:175], v[180:183], v[40:43]
	v_mfma_f32_16x16x32_bf16 v[28:31], v[164:167], v[188:191], v[28:31]
	v_mfma_f32_16x16x32_bf16 v[24:27], v[172:175], v[188:191], v[24:27]
	v_mfma_f32_16x16x32_bf16 v[12:15], v[164:167], v[198:201], v[12:15]
	v_mfma_f32_16x16x32_bf16 v[8:11], v[172:175], v[198:201], v[8:11]
	v_mfma_f32_16x16x32_bf16 v[4:7], v[164:167], v[206:209], v[4:7]
	v_mfma_f32_16x16x32_bf16 v[0:3], v[172:175], v[206:209], v[0:3]
	s_setprio 0
	s_barrier
	s_add_i32 s39, 0, 0x18000
	v_add_u32_e32 v143, s39, v141
	s_add_i32 s40, 0, 0x1c000
	ds_read_b128 v[144:147], v143
	ds_read_b128 v[148:151], v143 offset:1024
	ds_read_b128 v[152:155], v143 offset:2048
	ds_read_b128 v[156:159], v143 offset:3072
	v_add_u32_e32 v143, s40, v141
	ds_read_b128 v[160:163], v143
	ds_read_b128 v[164:167], v143 offset:1024
	ds_read_b128 v[168:171], v143 offset:2048
	ds_read_b128 v[172:175], v143 offset:3072
	s_add_u32 s12, s18, 0x160000
	s_addc_u32 s13, s19, 0
	s_mov_b32 m0, s23
	v_lshl_add_u64 v[226:227], s[12:13], 0, v[132:133]
	ds_read_b128 v[176:179], v142 offset:32768
	ds_read_b128 v[180:183], v142 offset:33792
	ds_read_b128 v[184:187], v142 offset:34816
	ds_read_b128 v[188:191], v142 offset:35840
	ds_read_b128 v[194:197], v142 offset:36864
	ds_read_b128 v[198:201], v142 offset:37888
	ds_read_b128 v[202:205], v142 offset:38912
	ds_read_b128 v[206:209], v142 offset:39936
	global_load_lds_dwordx4 v[226:227], off
	v_lshl_add_u64 v[226:227], s[12:13], 0, v[130:131]
	s_mov_b32 m0, s24
	s_nop 0
	global_load_lds_dwordx4 v[226:227], off
	s_waitcnt vmcnt(8)
	s_waitcnt lgkmcnt(0)
	s_setprio 1
	s_barrier
	v_mfma_f32_16x16x32_bf16 v[124:127], v[144:147], v[176:179], v[124:127]
	v_mfma_f32_16x16x32_bf16 v[120:123], v[152:155], v[176:179], v[120:123]
	v_mfma_f32_16x16x32_bf16 v[116:119], v[144:147], v[184:187], v[116:119]
	v_mfma_f32_16x16x32_bf16 v[112:115], v[152:155], v[184:187], v[112:115]
	v_mfma_f32_16x16x32_bf16 v[100:103], v[144:147], v[194:197], v[100:103]
	v_mfma_f32_16x16x32_bf16 v[96:99], v[152:155], v[194:197], v[96:99]
	v_mfma_f32_16x16x32_bf16 v[84:87], v[144:147], v[202:205], v[84:87]
	v_mfma_f32_16x16x32_bf16 v[80:83], v[152:155], v[202:205], v[80:83]
	v_mfma_f32_16x16x32_bf16 v[124:127], v[148:151], v[180:183], v[124:127]
	v_mfma_f32_16x16x32_bf16 v[120:123], v[156:159], v[180:183], v[120:123]
	v_mfma_f32_16x16x32_bf16 v[116:119], v[148:151], v[188:191], v[116:119]
	v_mfma_f32_16x16x32_bf16 v[112:115], v[156:159], v[188:191], v[112:115]
	v_mfma_f32_16x16x32_bf16 v[100:103], v[148:151], v[198:201], v[100:103]
	v_mfma_f32_16x16x32_bf16 v[96:99], v[156:159], v[198:201], v[96:99]
	v_mfma_f32_16x16x32_bf16 v[84:87], v[148:151], v[206:209], v[84:87]
	v_mfma_f32_16x16x32_bf16 v[80:83], v[156:159], v[206:209], v[80:83]
	v_mfma_f32_16x16x32_bf16 v[108:111], v[160:163], v[176:179], v[108:111]
	v_mfma_f32_16x16x32_bf16 v[104:107], v[168:171], v[176:179], v[104:107]
	v_mfma_f32_16x16x32_bf16 v[92:95], v[160:163], v[184:187], v[92:95]
	v_mfma_f32_16x16x32_bf16 v[88:91], v[168:171], v[184:187], v[88:91]
	v_mfma_f32_16x16x32_bf16 v[76:79], v[160:163], v[194:197], v[76:79]
	v_mfma_f32_16x16x32_bf16 v[72:75], v[168:171], v[194:197], v[72:75]
	v_mfma_f32_16x16x32_bf16 v[68:71], v[160:163], v[202:205], v[68:71]
	v_mfma_f32_16x16x32_bf16 v[64:67], v[168:171], v[202:205], v[64:67]
	v_mfma_f32_16x16x32_bf16 v[108:111], v[164:167], v[180:183], v[108:111]
	v_mfma_f32_16x16x32_bf16 v[104:107], v[172:175], v[180:183], v[104:107]
	v_mfma_f32_16x16x32_bf16 v[92:95], v[164:167], v[188:191], v[92:95]
	v_mfma_f32_16x16x32_bf16 v[88:91], v[172:175], v[188:191], v[88:91]
	v_mfma_f32_16x16x32_bf16 v[76:79], v[164:167], v[198:201], v[76:79]
	v_mfma_f32_16x16x32_bf16 v[72:75], v[172:175], v[198:201], v[72:75]
	v_mfma_f32_16x16x32_bf16 v[68:71], v[164:167], v[206:209], v[68:71]
	v_mfma_f32_16x16x32_bf16 v[64:67], v[172:175], v[206:209], v[64:67]
	s_setprio 0
	s_barrier
; #define STAGE_A(bufoff, gbase) STAGEX(bufoff, gbase, voffA)
; #define STAGE_B(bufoff, gbase) STAGEX(bufoff, gbase, voffB)
; #define LDA(dst, b, h) do { _Pragma("unroll") for (int m = 0; m < 4; ++m) _Pragma("unroll") for (int k = 0; k < 2; ++k) dst[m][k] = *(const __attribute__((address_space(3))) bf16x8*)(lds + SA(b, h) + aoff + m * 2048 + k * 1024); } while (0)
; #define LDB(dst, b, h) do { _Pragma("unroll") for (int n = 0; n < 2; ++n) _Pragma("unroll") for (int k = 0; k < 2; ++k) dst[n][k] = *(const __attribute__((address_space(3))) bf16x8*)(lds + SB_(b, h) + boff + n * 2048 + k * 1024); } while (0)
; #define MMA(ai, bj, At, Bt_) do { __builtin_amdgcn_s_setprio(1); _Pragma("unroll") for (int m = 0; m < 4; ++m) _Pragma("unroll") for (int n = 0; n < 2; ++n) _Pragma("unroll") for (int k = 0; k < 2; ++k) \
;       acc[ai][bj][m][n] = __builtin_amdgcn_mfma_f32_16x16x32_bf16(Bt_[n][k], At[m][k], acc[ai][bj][m][n], 0, 0, 0); \
;     __builtin_amdgcn_s_setprio(0); } while (0)
; #define WAIT_V(n) asm volatile("s_waitcnt vmcnt(" #n ")" ::: "memory")
; #define BAR __builtin_amdgcn_s_barrier()
; template <int MODE>
; DEV void gemm_phase(const bf16_t* __restrict__ A, const bf16_t* __restrict__ Bt, int M, int N, int K, bf16_t* __restrict__ Out, int ldo,
;                     const float* __restrict__ rstd, const float* __restrict__ rope) {
;     ...
;     for (int t = 0; t < nt; t += 2) {
;       const bool last = (t == nt - 2);
;       const char* a1 = cA + (size_t)(t + 1) * 128;
;       const char* a2 = last ? nA : cA + (size_t)(t + 2) * 128; const char* b2 = last ? nB : cB + (size_t)(t + 2) * 128;
;       const char* a3 = a2 + 128; const char* b3 = b2 + 128;
;       LDB(B0, 0, 0); LDB(B1, 0, 1); SCHED; LDA(At, 0, 0); STAGE_A(SA(1, 1), a1 + hstep);
;       WAIT_V(8); WAIT_L(0); BAR; MMA(0, 0, At, B0); MMA(0, 1, At, B1); BAR; SCHED;
;       LDA(At, 0, 1); STAGE_B(SB_(0, 0), b2); STAGE_B(SB_(0, 1), b2 + hstep); STAGE_A(SA(0, 0), a2);
;       WAIT_V(8); WAIT_L(0); BAR; MMA(1, 0, At, B0); MMA(1, 1, At, B1); BAR; SCHED;
;       LDB(B0, 1, 0); LDB(B1, 1, 1); SCHED; LDA(At, 1, 0); STAGE_A(SA(0, 1), a2 + hstep);
;       WAIT_V(8); WAIT_L(0); BAR; MMA(0, 0, At, B0); MMA(0, 1, At, B1); BAR; SCHED;
;       LDA(At, 1, 1); STAGE_B(SB_(1, 0), b3); STAGE_B(SB_(1, 1), b3 + hstep); STAGE_A(SA(1, 0), a3);
;       WAIT_V(8); WAIT_L(0); BAR; MMA(1, 0, At, B0); MMA(1, 1, At, B1); BAR; SCHED;
	s_add_i32 s12, s39, s20
	v_lshl_add_u64 v[212:213], v[212:213], 0, s[42:43]
	s_mov_b32 m0, s12
	ds_read_b128 v[176:179], v142 offset:49152
	ds_read_b128 v[180:183], v142 offset:50176
	ds_read_b128 v[184:187], v142 offset:51200
	ds_read_b128 v[188:191], v142 offset:52224
	ds_read_b128 v[194:197], v142 offset:53248
	ds_read_b128 v[198:201], v142 offset:54272
	ds_read_b128 v[202:205], v142 offset:55296
	ds_read_b128 v[206:209], v142 offset:56320
	global_load_lds_dwordx4 v[212:213], off
	s_add_i32 m0, s12, 0x2000
	s_add_u32 s12, s16, 0x160080
	v_lshl_add_u64 v[212:213], v[214:215], 0, s[42:43]
	s_addc_u32 s13, s17, 0
	s_add_i32 s16, s40, s20
	global_load_lds_dwordx4 v[212:213], off
	v_lshl_add_u64 v[212:213], s[12:13], 0, v[192:193]
	s_mov_b32 m0, s16
	s_nop 0
	global_load_lds_dwordx4 v[212:213], off
	v_lshl_add_u64 v[212:213], s[12:13], 0, v[128:129]
	s_add_i32 m0, s16, 0x2000
	s_nop 0
	global_load_lds_dwordx4 v[212:213], off
	v_lshl_add_u64 v[212:213], v[222:223], 0, s[42:43]
	s_mov_b32 m0, s25
	s_nop 0
	global_load_lds_dwordx4 v[212:213], off
	v_lshl_add_u64 v[212:213], v[224:225], 0, s[42:43]
	s_mov_b32 m0, s26
	s_nop 0
	global_load_lds_dwordx4 v[212:213], off
	s_waitcnt vmcnt(8)
	s_waitcnt lgkmcnt(0)
	s_setprio 1
	s_barrier
	v_mfma_f32_16x16x32_bf16 v[60:63], v[144:147], v[176:179], v[60:63]
	v_mfma_f32_16x16x32_bf16 v[56:59], v[152:155], v[176:179], v[56:59]
	v_mfma_f32_16x16x32_bf16 v[52:55], v[144:147], v[184:187], v[52:55]
	v_mfma_f32_16x16x32_bf16 v[48:51], v[152:155], v[184:187], v[48:51]
	v_mfma_f32_16x16x32_bf16 v[36:39], v[144:147], v[194:197], v[36:39]
	v_mfma_f32_16x16x32_bf16 v[32:35], v[152:155], v[194:197], v[32:35]
	v_mfma_f32_16x16x32_bf16 v[20:23], v[144:147], v[202:205], v[20:23]
	v_mfma_f32_16x16x32_bf16 v[16:19], v[152:155], v[202:205], v[16:19]
	v_mfma_f32_16x16x32_bf16 v[60:63], v[148:151], v[180:183], v[60:63]
	v_mfma_f32_16x16x32_bf16 v[56:59], v[156:159], v[180:183], v[56:59]
	v_mfma_f32_16x16x32_bf16 v[52:55], v[148:151], v[188:191], v[52:55]
	v_mfma_f32_16x16x32_bf16 v[48:51], v[156:159], v[188:191], v[48:51]
	v_mfma_f32_16x16x32_bf16 v[36:39], v[148:151], v[198:201], v[36:39]
	v_mfma_f32_16x16x32_bf16 v[32:35], v[156:159], v[198:201], v[32:35]
	v_mfma_f32_16x16x32_bf16 v[20:23], v[148:151], v[206:209], v[20:23]
	v_mfma_f32_16x16x32_bf16 v[16:19], v[156:159], v[206:209], v[16:19]
	v_mfma_f32_16x16x32_bf16 v[44:47], v[160:163], v[176:179], v[44:47]
	v_mfma_f32_16x16x32_bf16 v[40:43], v[168:171], v[176:179], v[40:43]
	v_mfma_f32_16x16x32_bf16 v[28:31], v[160:163], v[184:187], v[28:31]
	v_mfma_f32_16x16x32_bf16 v[24:27], v[168:171], v[184:187], v[24:27]
	v_mfma_f32_16x16x32_bf16 v[12:15], v[160:163], v[194:197], v[12:15]
	v_mfma_f32_16x16x32_bf16 v[8:11], v[168:171], v[194:197], v[8:11]
	v_mfma_f32_16x16x32_bf16 v[4:7], v[160:163], v[202:205], v[4:7]
	v_mfma_f32_16x16x32_bf16 v[0:3], v[168:171], v[202:205], v[0:3]
	v_mfma_f32_16x16x32_bf16 v[44:47], v[164:167], v[180:183], v[44:47]
	v_mfma_f32_16x16x32_bf16 v[40:43], v[172:175], v[180:183], v[40:43]
	v_mfma_f32_16x16x32_bf16 v[28:31], v[164:167], v[188:191], v[28:31]
	v_mfma_f32_16x16x32_bf16 v[24:27], v[172:175], v[188:191], v[24:27]
	v_mfma_f32_16x16x32_bf16 v[12:15], v[164:167], v[198:201], v[12:15]
	v_mfma_f32_16x16x32_bf16 v[8:11], v[172:175], v[198:201], v[8:11]
	v_mfma_f32_16x16x32_bf16 v[4:7], v[164:167], v[206:209], v[4:7]
	v_mfma_f32_16x16x32_bf16 v[0:3], v[172:175], v[206:209], v[0:3]
	s_setprio 0
	s_barrier
	s_add_i32 s38, s38, 2
	s_add_u32 s36, s36, 0x100
	s_addc_u32 s37, s37, 0
	s_cmpk_gt_u32 s38, 0x55
	s_mov_b64 s[12:13], s[14:15]
	s_cbranch_scc0 .LBB0_690
	s_and_b64 vcc, exec, s[4:5]
	s_cbranch_vccz .LBB0_693
	s_barrier
